# speedup vs baseline: 1.0205x; 1.0205x over previous
; __device__ __forceinline__ void ins16(u32 (&top)[16], u32 v) {
; #pragma unroll
;   for (int j = 0; j < 16; ++j) {
;     u32 hi = max(top[j], v);
;     v = min(top[j], v);
;     top[j] = hi;
;   }
; }
; __device__ void topk_phase(const Params& p) {
;     ...
;         for (int kp = 0; kp < 2; ++kp) {
;           f32x16 acc[2] = {zero16(), zero16()};
; #pragma unroll 4
;           for (int ks = 0; ks < 8; ++ks) {
;             s16x8 bq = *(const s16x8*)(qsrc + ks * 16);
; #pragma unroll
;             for (int kt = 0; kt < 2; ++kt) {
;               s16x8 ak = *(const s16x8*)(ksrc + (size_t)(kp * 2 + kt) * 32 * 128 + ks * 16);
;               acc[kt] = mfma32(ak, bq, acc[kt]);
;             }
;           }
;           const u32 kbase = (u32)(kp * 64 + 4 * lh);
; #pragma unroll
;           for (int kt = 0; kt < 2; ++kt)
; #pragma unroll
;             for (int r = 0; r < 16; ++r) {
;               const u32 key = (u32)(kt * 32 + (r & 3) + 8 * (r >> 2)) + kbase;
;               const u32 v = (ord_enc(acc[kt][r]) | 127u) ^ key;
;               ins16(top, v);
;             }
.LBB0_784:
	v_lshl_add_u64 v[102:103], v[52:53], 0, s[14:15]
	v_lshl_add_u64 v[100:101], v[50:51], 0, s[14:15]
	global_load_dwordx4 v[76:79], v[102:103], off
	global_load_dwordx4 v[80:83], v[100:101], off
	v_add_co_u32_e32 v104, vcc, s17, v102
	s_add_u32 s14, s14, 0x80
	s_nop 0
	v_addc_co_u32_e32 v105, vcc, 0, v103, vcc
	global_load_dwordx4 v[84:87], v[100:101], off offset:32
	global_load_dwordx4 v[88:91], v[102:103], off offset:32
	global_load_dwordx4 v[92:95], v[102:103], off offset:64
	global_load_dwordx4 v[96:99], v[104:105], off
	s_addc_u32 s15, s15, 0
	s_cmpk_eq_i32 s14, 0x100
	s_waitcnt vmcnt(4)
	v_mfma_f32_32x32x16_bf16 v[16:31], v[76:79], v[80:83], v[16:31]
	global_load_dwordx4 v[76:79], v[104:105], off offset:32
	s_waitcnt vmcnt(1)
	v_mfma_f32_32x32x16_bf16 v[0:15], v[96:99], v[80:83], v[0:15]
	global_load_dwordx4 v[80:83], v[100:101], off offset:64
	v_mfma_f32_32x32x16_bf16 v[16:31], v[88:91], v[84:87], v[16:31]
	global_load_dwordx4 v[88:91], v[104:105], off offset:64
	s_waitcnt vmcnt(1)
	v_mfma_f32_32x32x16_bf16 v[16:31], v[92:95], v[80:83], v[16:31]
	v_mfma_f32_32x32x16_bf16 v[0:15], v[76:79], v[84:87], v[0:15]
	global_load_dwordx4 v[76:79], v[102:103], off offset:96
	global_load_dwordx4 v[84:87], v[100:101], off offset:96
	global_load_dwordx4 v[92:95], v[104:105], off offset:96
	s_waitcnt vmcnt(3)
	v_mfma_f32_32x32x16_bf16 v[0:15], v[88:91], v[80:83], v[0:15]
	s_waitcnt vmcnt(1)
	v_mfma_f32_32x32x16_bf16 v[16:31], v[76:79], v[84:87], v[16:31]
	s_waitcnt vmcnt(0)
	v_mfma_f32_32x32x16_bf16 v[0:15], v[92:95], v[84:87], v[0:15]
	s_cbranch_scc0 .LBB0_784
	s_nop 8
	v_ashrrev_i32_e32 v53, 31, v16
	v_lshl_or_b32 v52, s4, 6, v54
	v_bitop3_b32 v16, v53, v16, s18 bitop3:0x36
	v_bitop3_b32 v16, v16, v52, s19 bitop3:0x36
	v_max_u32_e32 v53, v63, v16
	v_min_u32_e32 v16, v63, v16
	v_max_u32_e32 v63, v66, v16
	v_med3_u32 v66, v66, v43, v16
	v_med3_u32 v43, v43, v68, v16
	v_med3_u32 v68, v68, v61, v16
	v_med3_u32 v61, v61, v70, v16
	v_med3_u32 v70, v70, v60, v16
	v_med3_u32 v60, v60, v62, v16
	v_med3_u32 v62, v62, v34, v16
	v_med3_u32 v34, v34, v71, v16
	v_med3_u32 v71, v71, v64, v16
	v_med3_u32 v64, v64, v72, v16
	v_med3_u32 v72, v72, v65, v16
	v_med3_u32 v65, v65, v73, v16
	v_ashrrev_i32_e32 v75, 31, v17
	v_med3_u32 v73, v73, v67, v16
	v_min_u32_e32 v16, v67, v16
	v_or_b32_e32 v67, 1, v52
	v_bitop3_b32 v17, v75, v17, s18 bitop3:0x36
	v_bitop3_b32 v17, v17, v67, s19 bitop3:0x36
	v_max_u32_e32 v67, v53, v17
	v_min_u32_e32 v17, v53, v17
	v_max_u32_e32 v53, v63, v17
	v_med3_u32 v63, v63, v66, v17
	v_med3_u32 v66, v66, v43, v17
	v_med3_u32 v43, v43, v68, v17
	v_med3_u32 v68, v68, v61, v17
	v_med3_u32 v61, v61, v70, v17
	v_med3_u32 v70, v70, v60, v17
	v_med3_u32 v60, v60, v62, v17
	v_med3_u32 v62, v62, v34, v17
	v_med3_u32 v34, v34, v71, v17
	v_med3_u32 v71, v71, v64, v17
	v_med3_u32 v64, v64, v72, v17
	v_med3_u32 v72, v72, v65, v17
	v_med3_u32 v65, v65, v73, v17
	v_min_u32_e32 v17, v73, v17
	v_max3_u32 v16, v69, v16, v17
	v_ashrrev_i32_e32 v69, 31, v18
	v_or_b32_e32 v17, 2, v52
	v_bitop3_b32 v18, v69, v18, s18 bitop3:0x36
	v_bitop3_b32 v17, v18, v17, s19 bitop3:0x36
	v_max_u32_e32 v18, v67, v17
	v_min_u32_e32 v17, v67, v17
	v_max_u32_e32 v67, v53, v17
	v_min_u32_e32 v17, v53, v17
	v_max_u32_e32 v53, v63, v17
	v_min_u32_e32 v17, v63, v17
	v_max_u32_e32 v63, v66, v17
	v_min_u32_e32 v17, v66, v17
	v_max_u32_e32 v66, v43, v17
	v_min_u32_e32 v17, v43, v17
	v_max_u32_e32 v43, v68, v17
	v_min_u32_e32 v17, v68, v17
	v_max_u32_e32 v68, v61, v17
	v_min_u32_e32 v17, v61, v17
	v_max_u32_e32 v61, v70, v17
	v_min_u32_e32 v17, v70, v17
	v_max_u32_e32 v69, v60, v17
	v_min_u32_e32 v17, v60, v17
	v_max_u32_e32 v60, v62, v17
	v_min_u32_e32 v17, v62, v17
	v_max_u32_e32 v62, v34, v17
	v_min_u32_e32 v17, v34, v17
	v_max_u32_e32 v34, v71, v17
	v_min_u32_e32 v17, v71, v17
	v_max_u32_e32 v70, v64, v17
	v_min_u32_e32 v17, v64, v17
	v_max_u32_e32 v64, v72, v17
	v_min_u32_e32 v17, v72, v17
	v_ashrrev_i32_e32 v72, 31, v19
	v_max_u32_e32 v71, v65, v17
	v_min_u32_e32 v17, v65, v17
	v_or_b32_e32 v65, 3, v52
	v_bitop3_b32 v19, v72, v19, s18 bitop3:0x36
	v_bitop3_b32 v19, v19, v65, s19 bitop3:0x36
	v_max_u32_e32 v65, v18, v19
	v_min_u32_e32 v18, v18, v19
	v_max_u32_e32 v19, v67, v18
	v_med3_u32 v67, v67, v53, v18
	v_med3_u32 v53, v53, v63, v18
	v_med3_u32 v63, v63, v66, v18
	v_med3_u32 v66, v66, v43, v18
	v_med3_u32 v43, v43, v68, v18
	v_med3_u32 v68, v68, v61, v18
	v_med3_u32 v61, v61, v69, v18
	v_med3_u32 v69, v69, v60, v18
	v_med3_u32 v60, v60, v62, v18
	v_med3_u32 v62, v62, v34, v18
	v_med3_u32 v34, v34, v70, v18
	v_med3_u32 v70, v70, v64, v18
	v_med3_u32 v64, v64, v71, v18
	v_min_u32_e32 v18, v71, v18
	v_max3_u32 v16, v16, v17, v18
	v_ashrrev_i32_e32 v18, 31, v20
	v_or_b32_e32 v17, 8, v52
	v_bitop3_b32 v18, v18, v20, s18 bitop3:0x36
	v_bitop3_b32 v17, v18, v17, s19 bitop3:0x36
	v_max_u32_e32 v18, v65, v17
	v_min_u32_e32 v17, v65, v17
	v_max_u32_e32 v20, v19, v17
	v_min_u32_e32 v17, v19, v17
	v_max_u32_e32 v19, v67, v17
	v_min_u32_e32 v17, v67, v17
	v_max_u32_e32 v65, v53, v17
	v_min_u32_e32 v17, v53, v17
	v_max_u32_e32 v53, v63, v17
	v_min_u32_e32 v17, v63, v17
	v_max_u32_e32 v63, v66, v17
	v_min_u32_e32 v17, v66, v17
	v_max_u32_e32 v66, v43, v17
	v_min_u32_e32 v17, v43, v17
	v_max_u32_e32 v43, v68, v17
	v_min_u32_e32 v17, v68, v17
	v_max_u32_e32 v67, v61, v17
	v_min_u32_e32 v17, v61, v17
	v_max_u32_e32 v61, v69, v17
	v_min_u32_e32 v17, v69, v17
	v_max_u32_e32 v68, v60, v17
	v_min_u32_e32 v17, v60, v17
	v_max_u32_e32 v60, v62, v17
	v_min_u32_e32 v17, v62, v17
	v_max_u32_e32 v62, v34, v17
	v_min_u32_e32 v17, v34, v17
	v_max_u32_e32 v34, v70, v17
	v_min_u32_e32 v17, v70, v17
; __device__ __forceinline__ void ins16(u32 (&top)[16], u32 v) {
; #pragma unroll
;   for (int j = 0; j < 16; ++j) {
;     u32 hi = max(top[j], v);
;     v = min(top[j], v);
;     top[j] = hi;
;   }
; }
; __device__ void topk_phase(const Params& p) {
;     ...
;           const u32 kbase = (u32)(kp * 64 + 4 * lh);
; #pragma unroll
;           for (int kt = 0; kt < 2; ++kt)
; #pragma unroll
;             for (int r = 0; r < 16; ++r) {
;               const u32 key = (u32)(kt * 32 + (r & 3) + 8 * (r >> 2)) + kbase;
;               const u32 v = (ord_enc(acc[kt][r]) | 127u) ^ key;
;               ins16(top, v);
;             }
	v_ashrrev_i32_e32 v70, 31, v21
	v_max_u32_e32 v69, v64, v17
	v_min_u32_e32 v17, v64, v17
	v_or_b32_e32 v64, 9, v52
	v_bitop3_b32 v21, v70, v21, s18 bitop3:0x36
	v_bitop3_b32 v21, v21, v64, s19 bitop3:0x36
	v_max_u32_e32 v64, v18, v21
	v_min_u32_e32 v18, v18, v21
	v_max_u32_e32 v21, v20, v18
	v_med3_u32 v20, v20, v19, v18
	v_med3_u32 v19, v19, v65, v18
	v_med3_u32 v65, v65, v53, v18
	v_med3_u32 v53, v53, v63, v18
	v_med3_u32 v63, v63, v66, v18
	v_med3_u32 v66, v66, v43, v18
	v_med3_u32 v43, v43, v67, v18
	v_med3_u32 v67, v67, v61, v18
	v_med3_u32 v61, v61, v68, v18
	v_med3_u32 v68, v68, v60, v18
	v_med3_u32 v60, v60, v62, v18
	v_med3_u32 v62, v62, v34, v18
	v_med3_u32 v34, v34, v69, v18
	v_min_u32_e32 v18, v69, v18
	v_max3_u32 v16, v16, v17, v18
	v_ashrrev_i32_e32 v18, 31, v22
	v_or_b32_e32 v17, 10, v52
	v_bitop3_b32 v18, v18, v22, s18 bitop3:0x36
	v_bitop3_b32 v17, v18, v17, s19 bitop3:0x36
	v_max_u32_e32 v18, v64, v17
	v_min_u32_e32 v17, v64, v17
	v_max_u32_e32 v22, v21, v17
	v_med3_u32 v21, v21, v20, v17
	v_med3_u32 v20, v20, v19, v17
	v_med3_u32 v19, v19, v65, v17
	v_med3_u32 v64, v65, v53, v17
	v_med3_u32 v53, v53, v63, v17
	v_med3_u32 v63, v63, v66, v17
	v_med3_u32 v65, v66, v43, v17
	v_med3_u32 v43, v43, v67, v17
	v_med3_u32 v66, v67, v61, v17
	v_med3_u32 v61, v61, v68, v17
	v_med3_u32 v67, v68, v60, v17
	v_med3_u32 v60, v60, v62, v17
	v_ashrrev_i32_e32 v68, 31, v23
	v_med3_u32 v62, v62, v34, v17
	v_min_u32_e32 v17, v34, v17
	v_or_b32_e32 v34, 11, v52
	v_bitop3_b32 v23, v68, v23, s18 bitop3:0x36
	v_bitop3_b32 v23, v23, v34, s19 bitop3:0x36
	v_max_u32_e32 v34, v18, v23
	v_min_u32_e32 v18, v18, v23
	v_max_u32_e32 v23, v22, v18
	v_med3_u32 v22, v22, v21, v18
	v_med3_u32 v21, v21, v20, v18
	v_med3_u32 v20, v20, v19, v18
	v_med3_u32 v19, v19, v64, v18
	v_med3_u32 v64, v64, v53, v18
	v_med3_u32 v53, v53, v63, v18
	v_med3_u32 v63, v63, v65, v18
	v_med3_u32 v65, v65, v43, v18
	v_med3_u32 v43, v43, v66, v18
	v_med3_u32 v66, v66, v61, v18
	v_med3_u32 v61, v61, v67, v18
	v_med3_u32 v67, v67, v60, v18
	v_med3_u32 v60, v60, v62, v18
	v_min_u32_e32 v18, v62, v18
	v_max3_u32 v16, v16, v17, v18
	v_ashrrev_i32_e32 v18, 31, v24
	v_or_b32_e32 v17, 16, v52
	v_bitop3_b32 v18, v18, v24, s18 bitop3:0x36
	v_bitop3_b32 v17, v18, v17, s19 bitop3:0x36
	v_max_u32_e32 v18, v34, v17
	v_min_u32_e32 v17, v34, v17
	v_max_u32_e32 v24, v23, v17
	v_med3_u32 v23, v23, v22, v17
	v_med3_u32 v22, v22, v21, v17
	v_med3_u32 v21, v21, v20, v17
	v_med3_u32 v20, v20, v19, v17
	v_med3_u32 v19, v19, v64, v17
	v_med3_u32 v34, v64, v53, v17
	v_med3_u32 v53, v53, v63, v17
	v_med3_u32 v62, v63, v65, v17
	v_med3_u32 v63, v65, v43, v17
	v_med3_u32 v43, v43, v66, v17
	v_med3_u32 v64, v66, v61, v17
	v_med3_u32 v61, v61, v67, v17
	v_ashrrev_i32_e32 v66, 31, v25
	v_med3_u32 v65, v67, v60, v17
	v_min_u32_e32 v17, v60, v17
	v_or_b32_e32 v60, 17, v52
	v_bitop3_b32 v25, v66, v25, s18 bitop3:0x36
	v_bitop3_b32 v25, v25, v60, s19 bitop3:0x36
	v_max_u32_e32 v60, v18, v25
	v_min_u32_e32 v18, v18, v25
	v_max_u32_e32 v25, v24, v18
	v_med3_u32 v24, v24, v23, v18
	v_med3_u32 v23, v23, v22, v18
	v_med3_u32 v22, v22, v21, v18
	v_med3_u32 v21, v21, v20, v18
	v_med3_u32 v20, v20, v19, v18
	v_med3_u32 v19, v19, v34, v18
	v_med3_u32 v34, v34, v53, v18
	v_med3_u32 v53, v53, v62, v18
	v_med3_u32 v62, v62, v63, v18
	v_med3_u32 v63, v63, v43, v18
	v_med3_u32 v43, v43, v64, v18
	v_med3_u32 v64, v64, v61, v18
	v_med3_u32 v61, v61, v65, v18
	v_min_u32_e32 v18, v65, v18
	v_max3_u32 v16, v16, v17, v18
	v_ashrrev_i32_e32 v18, 31, v26
	v_or_b32_e32 v17, 18, v52
	v_bitop3_b32 v18, v18, v26, s18 bitop3:0x36
	v_bitop3_b32 v17, v18, v17, s19 bitop3:0x36
	v_max_u32_e32 v18, v60, v17
	v_min_u32_e32 v17, v60, v17
	v_max_u32_e32 v26, v25, v17
	v_min_u32_e32 v17, v25, v17
	v_max_u32_e32 v25, v24, v17
	v_min_u32_e32 v17, v24, v17
	v_max_u32_e32 v24, v23, v17
	v_min_u32_e32 v17, v23, v17
	v_max_u32_e32 v23, v22, v17
	v_min_u32_e32 v17, v22, v17
	v_max_u32_e32 v22, v21, v17
	v_min_u32_e32 v17, v21, v17
	v_max_u32_e32 v21, v20, v17
	v_min_u32_e32 v17, v20, v17
	v_max_u32_e32 v20, v19, v17
	v_min_u32_e32 v17, v19, v17
	v_max_u32_e32 v19, v34, v17
	v_min_u32_e32 v17, v34, v17
	v_max_u32_e32 v34, v53, v17
	v_min_u32_e32 v17, v53, v17
	v_max_u32_e32 v53, v62, v17
	v_min_u32_e32 v17, v62, v17
	v_max_u32_e32 v60, v63, v17
	v_min_u32_e32 v17, v63, v17
	v_max_u32_e32 v62, v43, v17
	v_min_u32_e32 v17, v43, v17
	v_max_u32_e32 v43, v64, v17
	v_min_u32_e32 v17, v64, v17
	v_ashrrev_i32_e32 v64, 31, v27
	v_max_u32_e32 v63, v61, v17
	v_min_u32_e32 v17, v61, v17
	v_or_b32_e32 v61, 19, v52
	v_bitop3_b32 v27, v64, v27, s18 bitop3:0x36
	v_bitop3_b32 v27, v27, v61, s19 bitop3:0x36
	v_max_u32_e32 v61, v18, v27
	v_min_u32_e32 v18, v18, v27
	v_max_u32_e32 v27, v26, v18
	v_med3_u32 v26, v26, v25, v18
	v_med3_u32 v25, v25, v24, v18
	v_med3_u32 v24, v24, v23, v18
	v_med3_u32 v23, v23, v22, v18
	v_med3_u32 v22, v22, v21, v18
	v_med3_u32 v21, v21, v20, v18
	v_med3_u32 v20, v20, v19, v18
	v_med3_u32 v19, v19, v34, v18
	v_med3_u32 v34, v34, v53, v18
	v_med3_u32 v53, v53, v60, v18
	v_med3_u32 v60, v60, v62, v18
	v_med3_u32 v62, v62, v43, v18
	v_med3_u32 v43, v43, v63, v18
	v_min_u32_e32 v18, v63, v18
	v_max3_u32 v16, v16, v17, v18
	v_ashrrev_i32_e32 v18, 31, v28
	v_or_b32_e32 v17, 24, v52
	v_bitop3_b32 v18, v18, v28, s18 bitop3:0x36
	v_bitop3_b32 v17, v18, v17, s19 bitop3:0x36
	v_max_u32_e32 v18, v61, v17
	v_min_u32_e32 v17, v61, v17
	v_max_u32_e32 v28, v27, v17
	v_min_u32_e32 v17, v27, v17
	v_max_u32_e32 v27, v26, v17
	v_min_u32_e32 v17, v26, v17
	v_max_u32_e32 v26, v25, v17
	v_min_u32_e32 v17, v25, v17
	v_max_u32_e32 v25, v24, v17
	v_min_u32_e32 v17, v24, v17
; __device__ __forceinline__ void ins16(u32 (&top)[16], u32 v) {
; #pragma unroll
;   for (int j = 0; j < 16; ++j) {
;     u32 hi = max(top[j], v);
;     v = min(top[j], v);
;     top[j] = hi;
;   }
; }
; __device__ void topk_phase(const Params& p) {
;     ...
;           const u32 kbase = (u32)(kp * 64 + 4 * lh);
; #pragma unroll
;           for (int kt = 0; kt < 2; ++kt)
; #pragma unroll
;             for (int r = 0; r < 16; ++r) {
;               const u32 key = (u32)(kt * 32 + (r & 3) + 8 * (r >> 2)) + kbase;
;               const u32 v = (ord_enc(acc[kt][r]) | 127u) ^ key;
;               ins16(top, v);
;             }
	v_max_u32_e32 v24, v23, v17
	v_min_u32_e32 v17, v23, v17
	v_max_u32_e32 v23, v22, v17
	v_min_u32_e32 v17, v22, v17
	v_max_u32_e32 v22, v21, v17
	v_min_u32_e32 v17, v21, v17
	v_max_u32_e32 v21, v20, v17
	v_min_u32_e32 v17, v20, v17
	v_max_u32_e32 v20, v19, v17
	v_min_u32_e32 v17, v19, v17
	v_max_u32_e32 v19, v34, v17
	v_min_u32_e32 v17, v34, v17
	v_max_u32_e32 v34, v53, v17
	v_min_u32_e32 v17, v53, v17
	v_max_u32_e32 v53, v60, v17
	v_min_u32_e32 v17, v60, v17
	v_max_u32_e32 v60, v62, v17
	v_min_u32_e32 v17, v62, v17
	v_ashrrev_i32_e32 v62, 31, v29
	v_max_u32_e32 v61, v43, v17
	v_min_u32_e32 v17, v43, v17
	v_or_b32_e32 v43, 25, v52
	v_bitop3_b32 v29, v62, v29, s18 bitop3:0x36
	v_bitop3_b32 v29, v29, v43, s19 bitop3:0x36
	v_max_u32_e32 v43, v18, v29
	v_min_u32_e32 v18, v18, v29
	v_max_u32_e32 v29, v28, v18
	v_med3_u32 v28, v28, v27, v18
	v_med3_u32 v27, v27, v26, v18
	v_med3_u32 v26, v26, v25, v18
	v_med3_u32 v25, v25, v24, v18
	v_med3_u32 v24, v24, v23, v18
	v_med3_u32 v23, v23, v22, v18
	v_med3_u32 v22, v22, v21, v18
	v_med3_u32 v21, v21, v20, v18
	v_med3_u32 v20, v20, v19, v18
	v_med3_u32 v19, v19, v34, v18
	v_med3_u32 v34, v34, v53, v18
	v_med3_u32 v53, v53, v60, v18
	v_med3_u32 v60, v60, v61, v18
	v_min_u32_e32 v18, v61, v18
	v_max3_u32 v16, v16, v17, v18
	v_ashrrev_i32_e32 v18, 31, v30
	v_or_b32_e32 v17, 26, v52
	v_bitop3_b32 v18, v18, v30, s18 bitop3:0x36
	v_bitop3_b32 v17, v18, v17, s19 bitop3:0x36
	v_max_u32_e32 v18, v43, v17
	v_min_u32_e32 v17, v43, v17
	v_max_u32_e32 v30, v29, v17
	v_med3_u32 v29, v29, v28, v17
	v_med3_u32 v28, v28, v27, v17
	v_med3_u32 v27, v27, v26, v17
	v_med3_u32 v26, v26, v25, v17
	v_med3_u32 v25, v25, v24, v17
	v_med3_u32 v24, v24, v23, v17
	v_med3_u32 v23, v23, v22, v17
	v_med3_u32 v22, v22, v21, v17
	v_med3_u32 v21, v21, v20, v17
	v_med3_u32 v20, v20, v19, v17
	v_med3_u32 v19, v19, v34, v17
	v_med3_u32 v34, v34, v53, v17
	v_med3_u32 v43, v53, v60, v17
	v_min_u32_e32 v17, v60, v17
	v_ashrrev_i32_e32 v60, 31, v31
	v_or_b32_e32 v53, 27, v52
	v_bitop3_b32 v31, v60, v31, s18 bitop3:0x36
	v_bitop3_b32 v31, v31, v53, s19 bitop3:0x36
	v_max_u32_e32 v53, v18, v31
	v_min_u32_e32 v18, v18, v31
	v_max_u32_e32 v31, v30, v18
	v_med3_u32 v30, v30, v29, v18
	v_med3_u32 v29, v29, v28, v18
	v_med3_u32 v28, v28, v27, v18
	v_med3_u32 v27, v27, v26, v18
	v_med3_u32 v26, v26, v25, v18
	v_med3_u32 v25, v25, v24, v18
	v_med3_u32 v24, v24, v23, v18
	v_med3_u32 v23, v23, v22, v18
	v_med3_u32 v22, v22, v21, v18
	v_med3_u32 v21, v21, v20, v18
	v_med3_u32 v20, v20, v19, v18
	v_med3_u32 v19, v19, v34, v18
	v_med3_u32 v34, v34, v43, v18
	v_min_u32_e32 v18, v43, v18
	v_max3_u32 v16, v16, v17, v18
	v_ashrrev_i32_e32 v18, 31, v0
	v_or_b32_e32 v17, 32, v52
	v_bitop3_b32 v0, v18, v0, s18 bitop3:0x36
	v_bitop3_b32 v0, v0, v17, s19 bitop3:0x36
	v_max_u32_e32 v17, v53, v0
	v_min_u32_e32 v0, v53, v0
	v_max_u32_e32 v18, v31, v0
	v_med3_u32 v31, v31, v30, v0
	v_med3_u32 v30, v30, v29, v0
	v_med3_u32 v29, v29, v28, v0
	v_med3_u32 v28, v28, v27, v0
	v_med3_u32 v27, v27, v26, v0
	v_med3_u32 v26, v26, v25, v0
	v_med3_u32 v25, v25, v24, v0
	v_med3_u32 v24, v24, v23, v0
	v_med3_u32 v23, v23, v22, v0
	v_med3_u32 v22, v22, v21, v0
	v_med3_u32 v21, v21, v20, v0
	v_med3_u32 v20, v20, v19, v0
	v_ashrrev_i32_e32 v43, 31, v1
	v_med3_u32 v19, v19, v34, v0
	v_min_u32_e32 v0, v34, v0
	v_or_b32_e32 v34, 33, v52
	v_bitop3_b32 v1, v43, v1, s18 bitop3:0x36
	v_bitop3_b32 v1, v1, v34, s19 bitop3:0x36
	v_max_u32_e32 v34, v17, v1
	v_min_u32_e32 v1, v17, v1
	v_max_u32_e32 v17, v18, v1
	v_med3_u32 v18, v18, v31, v1
	v_med3_u32 v31, v31, v30, v1
	v_med3_u32 v30, v30, v29, v1
	v_med3_u32 v29, v29, v28, v1
	v_med3_u32 v28, v28, v27, v1
	v_med3_u32 v27, v27, v26, v1
	v_med3_u32 v26, v26, v25, v1
	v_med3_u32 v25, v25, v24, v1
	v_med3_u32 v24, v24, v23, v1
	v_med3_u32 v23, v23, v22, v1
	v_med3_u32 v22, v22, v21, v1
	v_med3_u32 v21, v21, v20, v1
	v_med3_u32 v20, v20, v19, v1
	v_min_u32_e32 v1, v19, v1
	v_max3_u32 v0, v16, v0, v1
	v_ashrrev_i32_e32 v16, 31, v2
	v_or_b32_e32 v1, 34, v52
	v_bitop3_b32 v2, v16, v2, s18 bitop3:0x36
	v_bitop3_b32 v1, v2, v1, s19 bitop3:0x36
	v_max_u32_e32 v2, v34, v1
	v_min_u32_e32 v1, v34, v1
	v_max_u32_e32 v16, v17, v1
	v_med3_u32 v17, v17, v18, v1
	v_med3_u32 v18, v18, v31, v1
	v_med3_u32 v19, v31, v30, v1
	v_med3_u32 v30, v30, v29, v1
	v_med3_u32 v29, v29, v28, v1
	v_med3_u32 v28, v28, v27, v1
	v_med3_u32 v27, v27, v26, v1
	v_med3_u32 v26, v26, v25, v1
	v_med3_u32 v25, v25, v24, v1
	v_med3_u32 v24, v24, v23, v1
	v_med3_u32 v23, v23, v22, v1
	v_med3_u32 v22, v22, v21, v1
	v_ashrrev_i32_e32 v31, 31, v3
	v_med3_u32 v21, v21, v20, v1
	v_min_u32_e32 v1, v20, v1
	v_or_b32_e32 v20, 35, v52
	v_bitop3_b32 v3, v31, v3, s18 bitop3:0x36
	v_bitop3_b32 v3, v3, v20, s19 bitop3:0x36
	v_max_u32_e32 v20, v2, v3
	v_min_u32_e32 v2, v2, v3
	v_max_u32_e32 v3, v16, v2
	v_med3_u32 v16, v16, v17, v2
	v_med3_u32 v17, v17, v18, v2
	v_med3_u32 v18, v18, v19, v2
	v_med3_u32 v19, v19, v30, v2
	v_med3_u32 v30, v30, v29, v2
	v_med3_u32 v29, v29, v28, v2
	v_med3_u32 v28, v28, v27, v2
	v_med3_u32 v27, v27, v26, v2
	v_med3_u32 v26, v26, v25, v2
	v_med3_u32 v25, v25, v24, v2
	v_med3_u32 v24, v24, v23, v2
	v_med3_u32 v23, v23, v22, v2
	v_med3_u32 v22, v22, v21, v2
	v_min_u32_e32 v2, v21, v2
	v_max3_u32 v0, v0, v1, v2
	v_ashrrev_i32_e32 v2, 31, v4
	v_or_b32_e32 v1, 40, v52
	v_bitop3_b32 v2, v2, v4, s18 bitop3:0x36
	v_bitop3_b32 v1, v2, v1, s19 bitop3:0x36
	v_max_u32_e32 v2, v20, v1
	v_min_u32_e32 v1, v20, v1
	v_max_u32_e32 v4, v3, v1
	v_med3_u32 v3, v3, v16, v1
	v_med3_u32 v16, v16, v17, v1
	v_med3_u32 v17, v17, v18, v1
	v_med3_u32 v18, v18, v19, v1
	v_med3_u32 v19, v19, v30, v1
; __device__ __forceinline__ void ins16(u32 (&top)[16], u32 v) {
; #pragma unroll
;   for (int j = 0; j < 16; ++j) {
;     u32 hi = max(top[j], v);
;     v = min(top[j], v);
;     top[j] = hi;
;   }
; }
; __device__ void topk_phase(const Params& p) {
;     ...
;           const u32 kbase = (u32)(kp * 64 + 4 * lh);
; #pragma unroll
;           for (int kt = 0; kt < 2; ++kt)
; #pragma unroll
;             for (int r = 0; r < 16; ++r) {
;               const u32 key = (u32)(kt * 32 + (r & 3) + 8 * (r >> 2)) + kbase;
;               const u32 v = (ord_enc(acc[kt][r]) | 127u) ^ key;
;               ins16(top, v);
;             }
	v_med3_u32 v20, v30, v29, v1
	v_med3_u32 v21, v29, v28, v1
	v_med3_u32 v28, v28, v27, v1
	v_med3_u32 v27, v27, v26, v1
	v_med3_u32 v26, v26, v25, v1
	v_med3_u32 v25, v25, v24, v1
	v_med3_u32 v24, v24, v23, v1
	v_ashrrev_i32_e32 v29, 31, v5
	v_med3_u32 v23, v23, v22, v1
	v_min_u32_e32 v1, v22, v1
	v_or_b32_e32 v22, 41, v52
	v_bitop3_b32 v5, v29, v5, s18 bitop3:0x36
	v_bitop3_b32 v5, v5, v22, s19 bitop3:0x36
	v_max_u32_e32 v22, v2, v5
	v_min_u32_e32 v2, v2, v5
	v_max_u32_e32 v5, v4, v2
	v_med3_u32 v4, v4, v3, v2
	v_med3_u32 v3, v3, v16, v2
	v_med3_u32 v16, v16, v17, v2
	v_med3_u32 v17, v17, v18, v2
	v_med3_u32 v18, v18, v19, v2
	v_med3_u32 v19, v19, v20, v2
	v_med3_u32 v20, v20, v21, v2
	v_med3_u32 v21, v21, v28, v2
	v_med3_u32 v28, v28, v27, v2
	v_med3_u32 v27, v27, v26, v2
	v_med3_u32 v26, v26, v25, v2
	v_med3_u32 v25, v25, v24, v2
	v_med3_u32 v24, v24, v23, v2
	v_min_u32_e32 v2, v23, v2
	v_max3_u32 v0, v0, v1, v2
	v_ashrrev_i32_e32 v2, 31, v6
	v_or_b32_e32 v1, 42, v52
	v_bitop3_b32 v2, v2, v6, s18 bitop3:0x36
	v_bitop3_b32 v1, v2, v1, s19 bitop3:0x36
	v_max_u32_e32 v2, v22, v1
	v_min_u32_e32 v1, v22, v1
	v_max_u32_e32 v6, v5, v1
	v_med3_u32 v5, v5, v4, v1
	v_med3_u32 v4, v4, v3, v1
	v_med3_u32 v3, v3, v16, v1
	v_med3_u32 v16, v16, v17, v1
	v_med3_u32 v17, v17, v18, v1
	v_med3_u32 v18, v18, v19, v1
	v_med3_u32 v19, v19, v20, v1
	v_med3_u32 v20, v20, v21, v1
	v_med3_u32 v21, v21, v28, v1
	v_med3_u32 v22, v28, v27, v1
	v_med3_u32 v23, v27, v26, v1
	v_med3_u32 v26, v26, v25, v1
	v_ashrrev_i32_e32 v27, 31, v7
	v_med3_u32 v25, v25, v24, v1
	v_min_u32_e32 v1, v24, v1
	v_or_b32_e32 v24, 43, v52
	v_bitop3_b32 v7, v27, v7, s18 bitop3:0x36
	v_bitop3_b32 v7, v7, v24, s19 bitop3:0x36
	v_max_u32_e32 v24, v2, v7
	v_min_u32_e32 v2, v2, v7
	v_max_u32_e32 v7, v6, v2
	v_med3_u32 v6, v6, v5, v2
	v_med3_u32 v5, v5, v4, v2
	v_med3_u32 v4, v4, v3, v2
	v_med3_u32 v3, v3, v16, v2
	v_med3_u32 v16, v16, v17, v2
	v_med3_u32 v17, v17, v18, v2
	v_med3_u32 v18, v18, v19, v2
	v_med3_u32 v19, v19, v20, v2
	v_med3_u32 v20, v20, v21, v2
	v_med3_u32 v21, v21, v22, v2
	v_med3_u32 v22, v22, v23, v2
	v_med3_u32 v23, v23, v26, v2
	v_med3_u32 v26, v26, v25, v2
	v_min_u32_e32 v2, v25, v2
	v_max3_u32 v0, v0, v1, v2
	v_ashrrev_i32_e32 v2, 31, v8
	v_or_b32_e32 v1, 48, v52
	v_bitop3_b32 v2, v2, v8, s18 bitop3:0x36
	v_bitop3_b32 v1, v2, v1, s19 bitop3:0x36
	v_ashrrev_i32_e32 v25, 31, v9
	v_max_u32_e32 v2, v24, v1
	v_min_u32_e32 v1, v24, v1
	v_or_b32_e32 v24, 49, v52
	v_bitop3_b32 v9, v25, v9, s18 bitop3:0x36
	v_bitop3_b32 v9, v9, v24, s19 bitop3:0x36
	v_max_u32_e32 v8, v7, v1
	v_min_u32_e32 v1, v7, v1
	v_max_u32_e32 v24, v2, v9
	v_min_u32_e32 v2, v2, v9
	v_max_u32_e32 v7, v6, v1
	v_min_u32_e32 v1, v6, v1
	v_max_u32_e32 v9, v8, v2
	v_min_u32_e32 v2, v8, v2
	v_max_u32_e32 v6, v5, v1
	v_min_u32_e32 v1, v5, v1
	v_max_u32_e32 v8, v7, v2
	v_min_u32_e32 v2, v7, v2
	v_max_u32_e32 v5, v4, v1
	v_min_u32_e32 v1, v4, v1
	v_max_u32_e32 v7, v6, v2
	v_min_u32_e32 v2, v6, v2
	v_max_u32_e32 v4, v3, v1
	v_min_u32_e32 v1, v3, v1
	v_max_u32_e32 v6, v5, v2
	v_min_u32_e32 v2, v5, v2
	v_max_u32_e32 v3, v16, v1
	v_min_u32_e32 v1, v16, v1
	v_max_u32_e32 v5, v4, v2
	v_min_u32_e32 v2, v4, v2
	v_max_u32_e32 v16, v17, v1
	v_min_u32_e32 v1, v17, v1
	v_max_u32_e32 v4, v3, v2
	v_min_u32_e32 v2, v3, v2
	v_max_u32_e32 v17, v18, v1
	v_min_u32_e32 v1, v18, v1
	v_max_u32_e32 v3, v16, v2
	v_min_u32_e32 v2, v16, v2
	v_max_u32_e32 v18, v19, v1
	v_min_u32_e32 v1, v19, v1
	v_max_u32_e32 v16, v17, v2
	v_min_u32_e32 v2, v17, v2
	v_max_u32_e32 v19, v20, v1
	v_min_u32_e32 v1, v20, v1
	v_max_u32_e32 v17, v18, v2
	v_min_u32_e32 v2, v18, v2
	v_max_u32_e32 v20, v21, v1
	v_min_u32_e32 v1, v21, v1
	v_max_u32_e32 v18, v19, v2
	v_min_u32_e32 v2, v19, v2
	v_max_u32_e32 v21, v22, v1
	v_min_u32_e32 v1, v22, v1
	v_max_u32_e32 v19, v20, v2
	v_min_u32_e32 v2, v20, v2
	v_max_u32_e32 v22, v23, v1
	v_min_u32_e32 v1, v23, v1
	v_max_u32_e32 v20, v21, v2
	v_min_u32_e32 v2, v21, v2
	v_max_u32_e32 v23, v26, v1
	v_max_u32_e32 v21, v22, v2
	v_min_u32_e32 v2, v22, v2
	v_min_u32_e32 v1, v26, v1
	v_max_u32_e32 v22, v23, v2
	v_min_u32_e32 v2, v23, v2
	v_max3_u32 v0, v0, v1, v2
	v_ashrrev_i32_e32 v2, 31, v10
	v_or_b32_e32 v1, 50, v52
	v_bitop3_b32 v2, v2, v10, s18 bitop3:0x36
	v_bitop3_b32 v1, v2, v1, s19 bitop3:0x36
; __device__ void topk_phase(const Params& p) {
;     ...
;           const u32 kbase = (u32)(kp * 64 + 4 * lh);
; #pragma unroll
;           for (int kt = 0; kt < 2; ++kt)
; #pragma unroll
;             for (int r = 0; r < 16; ++r) {
;               const u32 key = (u32)(kt * 32 + (r & 3) + 8 * (r >> 2)) + kbase;
;               const u32 v = (ord_enc(acc[kt][r]) | 127u) ^ key;
;               ins16(top, v);
;             }
;         }
;         u32 mg[16];
; #pragma unroll
;         for (int j = 0; j < 16; ++j) {
;           u32 o = (u32)__shfl_xor((int)top[15 - j], 32);
;           mg[j] = max(top[j], o);
	v_max_u32_e32 v2, v24, v1
	v_min_u32_e32 v1, v24, v1
	v_max_u32_e32 v10, v9, v1
	v_med3_u32 v9, v9, v8, v1
	v_med3_u32 v8, v8, v7, v1
	v_med3_u32 v7, v7, v6, v1
	v_med3_u32 v6, v6, v5, v1
	v_med3_u32 v5, v5, v4, v1
	v_med3_u32 v4, v4, v3, v1
	v_med3_u32 v3, v3, v16, v1
	v_med3_u32 v16, v16, v17, v1
	v_med3_u32 v17, v17, v18, v1
	v_med3_u32 v18, v18, v19, v1
	v_med3_u32 v19, v19, v20, v1
	v_med3_u32 v20, v20, v21, v1
	v_ashrrev_i32_e32 v23, 31, v11
	v_med3_u32 v21, v21, v22, v1
	v_min_u32_e32 v1, v22, v1
	v_or_b32_e32 v22, 51, v52
	v_bitop3_b32 v11, v23, v11, s18 bitop3:0x36
	v_bitop3_b32 v11, v11, v22, s19 bitop3:0x36
	v_max_u32_e32 v22, v2, v11
	v_min_u32_e32 v2, v2, v11
	v_max_u32_e32 v11, v10, v2
	v_med3_u32 v10, v10, v9, v2
	v_med3_u32 v9, v9, v8, v2
	v_med3_u32 v8, v8, v7, v2
	v_med3_u32 v7, v7, v6, v2
	v_med3_u32 v6, v6, v5, v2
	v_med3_u32 v5, v5, v4, v2
	v_med3_u32 v4, v4, v3, v2
	v_med3_u32 v3, v3, v16, v2
	v_med3_u32 v16, v16, v17, v2
	v_med3_u32 v17, v17, v18, v2
	v_med3_u32 v18, v18, v19, v2
	v_med3_u32 v19, v19, v20, v2
	v_med3_u32 v20, v20, v21, v2
	v_min_u32_e32 v2, v21, v2
	v_max3_u32 v0, v0, v1, v2
	v_ashrrev_i32_e32 v2, 31, v12
	v_or_b32_e32 v1, 56, v52
	v_bitop3_b32 v2, v2, v12, s18 bitop3:0x36
	v_bitop3_b32 v1, v2, v1, s19 bitop3:0x36
	v_max_u32_e32 v2, v22, v1
	v_min_u32_e32 v1, v22, v1
	v_max_u32_e32 v12, v11, v1
	v_med3_u32 v11, v11, v10, v1
	v_med3_u32 v10, v10, v9, v1
	v_med3_u32 v9, v9, v8, v1
	v_med3_u32 v8, v8, v7, v1
	v_med3_u32 v7, v7, v6, v1
	v_med3_u32 v6, v6, v5, v1
	v_med3_u32 v5, v5, v4, v1
	v_med3_u32 v4, v4, v3, v1
	v_med3_u32 v3, v3, v16, v1
	v_med3_u32 v16, v16, v17, v1
	v_med3_u32 v17, v17, v18, v1
	v_med3_u32 v18, v18, v19, v1
	v_ashrrev_i32_e32 v21, 31, v13
	v_med3_u32 v19, v19, v20, v1
	v_min_u32_e32 v1, v20, v1
	v_or_b32_e32 v20, 57, v52
	v_bitop3_b32 v13, v21, v13, s18 bitop3:0x36
	v_bitop3_b32 v13, v13, v20, s19 bitop3:0x36
	v_max_u32_e32 v20, v2, v13
	v_min_u32_e32 v2, v2, v13
	v_max_u32_e32 v13, v12, v2
	v_med3_u32 v12, v12, v11, v2
	v_med3_u32 v11, v11, v10, v2
	v_med3_u32 v10, v10, v9, v2
	v_med3_u32 v9, v9, v8, v2
	v_med3_u32 v8, v8, v7, v2
	v_med3_u32 v7, v7, v6, v2
	v_med3_u32 v6, v6, v5, v2
	v_med3_u32 v5, v5, v4, v2
	v_med3_u32 v4, v4, v3, v2
	v_med3_u32 v3, v3, v16, v2
	v_med3_u32 v16, v16, v17, v2
	v_med3_u32 v17, v17, v18, v2
	v_med3_u32 v18, v18, v19, v2
	v_min_u32_e32 v2, v19, v2
	v_max3_u32 v0, v0, v1, v2
	v_ashrrev_i32_e32 v2, 31, v14
	v_or_b32_e32 v1, 58, v52
	v_bitop3_b32 v2, v2, v14, s18 bitop3:0x36
	v_bitop3_b32 v1, v2, v1, s19 bitop3:0x36
	v_max_u32_e32 v2, v20, v1
	v_min_u32_e32 v1, v20, v1
	v_max_u32_e32 v14, v13, v1
	v_med3_u32 v13, v13, v12, v1
	v_med3_u32 v12, v12, v11, v1
	v_med3_u32 v11, v11, v10, v1
	v_med3_u32 v10, v10, v9, v1
	v_med3_u32 v9, v9, v8, v1
	v_med3_u32 v8, v8, v7, v1
	v_med3_u32 v7, v7, v6, v1
	v_med3_u32 v6, v6, v5, v1
	v_med3_u32 v5, v5, v4, v1
	v_med3_u32 v4, v4, v3, v1
	v_med3_u32 v3, v3, v16, v1
	v_med3_u32 v16, v16, v17, v1
	v_ashrrev_i32_e32 v19, 31, v15
	v_med3_u32 v17, v17, v18, v1
	v_min_u32_e32 v1, v18, v1
	v_or_b32_e32 v18, 59, v52
	v_bitop3_b32 v15, v19, v15, s18 bitop3:0x36
	v_bitop3_b32 v15, v15, v18, s19 bitop3:0x36
	v_max_u32_e32 v63, v2, v15
	v_min_u32_e32 v2, v2, v15
	v_max_u32_e32 v66, v14, v2
	v_med3_u32 v43, v14, v13, v2
	v_med3_u32 v68, v13, v12, v2
	v_med3_u32 v61, v12, v11, v2
	v_med3_u32 v70, v11, v10, v2
	v_med3_u32 v60, v10, v9, v2
	v_med3_u32 v62, v9, v8, v2
	v_med3_u32 v34, v8, v7, v2
	v_med3_u32 v71, v7, v6, v2
	v_med3_u32 v64, v6, v5, v2
	v_med3_u32 v72, v5, v4, v2
	v_med3_u32 v65, v4, v3, v2
	v_med3_u32 v73, v3, v16, v2
	v_med3_u32 v67, v16, v17, v2
	v_min_u32_e32 v2, v17, v2
	s_mov_b32 s4, 1
	v_max3_u32 v69, v0, v1, v2
	s_mov_b64 s[14:15], 0
	s_and_b64 vcc, exec, s[10:11]
	s_cbranch_vccz .LBB0_783
	ds_bpermute_b32 v75, v55, v67
	ds_bpermute_b32 v74, v55, v60
	ds_bpermute_b32 v76, v55, v43
	s_mov_b32 s4, 0
	s_mov_b64 s[10:11], -1
	v_mov_b32_e32 v78, 0
	v_mov_b32_e32 v81, 0
	v_mov_b32_e32 v82, 0
	v_mov_b32_e32 v83, 0
	v_mov_b32_e32 v88, 0
	v_mov_b32_e32 v90, 0
	v_mov_b32_e32 v91, 0
	v_mov_b32_e32 v89, 0
	v_mov_b32_e32 v80, 0
	v_mov_b32_e32 v92, 0
	v_mov_b32_e32 v93, 0
	v_mov_b32_e32 v84, 0
	v_mov_b32_e32 v85, 0
	v_mov_b32_e32 v86, 0
	v_mov_b32_e32 v87, 0
	v_mov_b32_e32 v77, 0
	v_mov_b32_e32 v79, 0

; __device__ __forceinline__ void ins16(u32 (&top)[16], u32 v) {
; #pragma unroll
;   for (int j = 0; j < 16; ++j) {
;     u32 hi = max(top[j], v);
;     v = min(top[j], v);
;     top[j] = hi;
;   }
; }
; __device__ void topk_phase(const Params& p) {
;     ...
;         for (int kp = 0; kp < 2; ++kp) {
;           f32x16 acc[2] = {zero16(), zero16()};
; #pragma unroll 4
;           for (int ks = 0; ks < 8; ++ks) {
;             s16x8 bq = *(const s16x8*)(qsrc + ks * 16);
; #pragma unroll
;             for (int kt = 0; kt < 2; ++kt) {
;               s16x8 ak = *(const s16x8*)(ksrc + (size_t)(kp * 2 + kt) * 32 * 128 + ks * 16);
;               acc[kt] = mfma32(ak, bq, acc[kt]);
;             }
;           }
;           const u32 kbase = (u32)(kp * 64 + 4 * lh);
; #pragma unroll
;           for (int kt = 0; kt < 2; ++kt)
; #pragma unroll
;             for (int r = 0; r < 16; ++r) {
;               const u32 key = (u32)(kt * 32 + (r & 3) + 8 * (r >> 2)) + kbase;
;               const u32 v = (ord_enc(acc[kt][r]) | 127u) ^ key;
;               ins16(top, v);
;             }
.LBB0_788:
	v_lshl_add_u64 v[94:95], v[52:53], 0, s[14:15]
	v_add_co_u32_e32 v122, vcc, s20, v94
	v_lshl_add_u64 v[106:107], v[50:51], 0, s[14:15]
	s_nop 0
	v_addc_co_u32_e32 v123, vcc, 0, v95, vcc
	v_add_co_u32_e32 v124, vcc, s21, v94
	s_add_u32 s14, s14, 0x80
	s_nop 0
	v_addc_co_u32_e32 v125, vcc, 0, v95, vcc
	global_load_dwordx4 v[94:97], v[106:107], off offset:256
	global_load_dwordx4 v[98:101], v[106:107], off offset:288
	global_load_dwordx4 v[102:105], v[106:107], off offset:320
	s_nop 0
	global_load_dwordx4 v[106:109], v[106:107], off offset:352
	s_nop 0
	global_load_dwordx4 v[110:113], v[122:123], off
	global_load_dwordx4 v[114:117], v[124:125], off
	global_load_dwordx4 v[118:121], v[122:123], off offset:32
	s_addc_u32 s15, s15, 0
	s_cmpk_lg_i32 s14, 0x100
	s_waitcnt vmcnt(2)
	v_mfma_f32_32x32x16_bf16 v[16:31], v[110:113], v[94:97], v[16:31]
	global_load_dwordx4 v[110:113], v[124:125], off offset:32
	s_waitcnt vmcnt(2)
	v_mfma_f32_32x32x16_bf16 v[0:15], v[114:117], v[94:97], v[0:15]
	global_load_dwordx4 v[94:97], v[122:123], off offset:64
	global_load_dwordx4 v[114:117], v[124:125], off offset:64
	s_waitcnt vmcnt(3)
	v_mfma_f32_32x32x16_bf16 v[16:31], v[118:121], v[98:101], v[16:31]
	s_waitcnt vmcnt(2)
	v_mfma_f32_32x32x16_bf16 v[0:15], v[110:113], v[98:101], v[0:15]
	global_load_dwordx4 v[98:101], v[122:123], off offset:96
	s_waitcnt vmcnt(2)
	v_mfma_f32_32x32x16_bf16 v[16:31], v[94:97], v[102:105], v[16:31]
	global_load_dwordx4 v[94:97], v[124:125], off offset:96
	s_waitcnt vmcnt(2)
	v_mfma_f32_32x32x16_bf16 v[0:15], v[114:117], v[102:105], v[0:15]
	s_waitcnt vmcnt(1)
	v_mfma_f32_32x32x16_bf16 v[16:31], v[98:101], v[106:109], v[16:31]
	s_waitcnt vmcnt(0)
	v_mfma_f32_32x32x16_bf16 v[0:15], v[94:97], v[106:109], v[0:15]
	s_cbranch_scc1 .LBB0_788
	s_nop 8
	v_ashrrev_i32_e32 v53, 31, v16
	v_lshl_or_b32 v52, s4, 6, v54
	v_bitop3_b32 v16, v53, v16, s18 bitop3:0x36
	v_bitop3_b32 v16, v16, v52, s19 bitop3:0x36
	v_max_u32_e32 v53, v78, v16
	v_min_u32_e32 v16, v78, v16
	v_max_u32_e32 v78, v81, v16
	v_med3_u32 v81, v81, v82, v16
	v_med3_u32 v82, v82, v83, v16
	v_med3_u32 v83, v83, v88, v16
	v_med3_u32 v88, v88, v90, v16
	v_med3_u32 v90, v90, v91, v16
	v_med3_u32 v91, v91, v89, v16
	v_med3_u32 v89, v89, v80, v16
	v_med3_u32 v80, v80, v92, v16
	v_med3_u32 v92, v92, v93, v16
	v_med3_u32 v93, v93, v84, v16
	v_med3_u32 v84, v84, v85, v16
	v_med3_u32 v85, v85, v86, v16
	v_ashrrev_i32_e32 v94, 31, v17
	v_med3_u32 v86, v86, v87, v16
	v_min_u32_e32 v16, v87, v16
	v_or_b32_e32 v87, 1, v52
	v_bitop3_b32 v17, v94, v17, s18 bitop3:0x36
	v_bitop3_b32 v17, v17, v87, s19 bitop3:0x36
	v_max_u32_e32 v87, v53, v17
	v_min_u32_e32 v17, v53, v17
	v_max_u32_e32 v53, v78, v17
	v_med3_u32 v78, v78, v81, v17
	v_med3_u32 v81, v81, v82, v17
	v_med3_u32 v82, v82, v83, v17
	v_med3_u32 v83, v83, v88, v17
	v_med3_u32 v88, v88, v90, v17
	v_med3_u32 v90, v90, v91, v17
	v_med3_u32 v91, v91, v89, v17
	v_med3_u32 v89, v89, v80, v17
	v_med3_u32 v80, v80, v92, v17
	v_med3_u32 v92, v92, v93, v17
	v_med3_u32 v93, v93, v84, v17
	v_med3_u32 v84, v84, v85, v17
	v_med3_u32 v85, v85, v86, v17
	v_min_u32_e32 v17, v86, v17
	v_max3_u32 v16, v79, v16, v17
	v_ashrrev_i32_e32 v79, 31, v18
	v_or_b32_e32 v17, 2, v52
	v_bitop3_b32 v18, v79, v18, s18 bitop3:0x36
	v_bitop3_b32 v17, v18, v17, s19 bitop3:0x36
	v_max_u32_e32 v18, v87, v17
	v_min_u32_e32 v17, v87, v17
	v_max_u32_e32 v79, v53, v17
	v_med3_u32 v53, v53, v78, v17
	v_med3_u32 v78, v78, v81, v17
	v_med3_u32 v81, v81, v82, v17
	v_med3_u32 v82, v82, v83, v17
	v_med3_u32 v83, v83, v88, v17
	v_med3_u32 v86, v88, v90, v17
	v_med3_u32 v87, v90, v91, v17
	v_med3_u32 v88, v91, v89, v17
	v_med3_u32 v89, v89, v80, v17
	v_med3_u32 v80, v80, v92, v17
	v_med3_u32 v90, v92, v93, v17
	v_med3_u32 v91, v93, v84, v17
	v_ashrrev_i32_e32 v92, 31, v19
	v_med3_u32 v84, v84, v85, v17
	v_min_u32_e32 v17, v85, v17
	v_or_b32_e32 v85, 3, v52
	v_bitop3_b32 v19, v92, v19, s18 bitop3:0x36
	v_bitop3_b32 v19, v19, v85, s19 bitop3:0x36
	v_max_u32_e32 v85, v18, v19
	v_min_u32_e32 v18, v18, v19
	v_max_u32_e32 v19, v79, v18
	v_med3_u32 v79, v79, v53, v18
	v_med3_u32 v53, v53, v78, v18
	v_med3_u32 v78, v78, v81, v18
	v_med3_u32 v81, v81, v82, v18
	v_med3_u32 v82, v82, v83, v18
	v_med3_u32 v83, v83, v86, v18
	v_med3_u32 v86, v86, v87, v18
	v_med3_u32 v87, v87, v88, v18
	v_med3_u32 v88, v88, v89, v18
	v_med3_u32 v89, v89, v80, v18
	v_med3_u32 v80, v80, v90, v18
	v_med3_u32 v90, v90, v91, v18
	v_med3_u32 v91, v91, v84, v18
	v_min_u32_e32 v18, v84, v18
	v_max3_u32 v16, v16, v17, v18
	v_ashrrev_i32_e32 v18, 31, v20
	v_or_b32_e32 v17, 8, v52
	v_bitop3_b32 v18, v18, v20, s18 bitop3:0x36
	v_bitop3_b32 v17, v18, v17, s19 bitop3:0x36
	v_max_u32_e32 v18, v85, v17
	v_min_u32_e32 v17, v85, v17
	v_max_u32_e32 v20, v19, v17
	v_med3_u32 v19, v19, v79, v17
	v_med3_u32 v79, v79, v53, v17
	v_med3_u32 v53, v53, v78, v17
	v_med3_u32 v78, v78, v81, v17
	v_med3_u32 v81, v81, v82, v17
	v_med3_u32 v82, v82, v83, v17
	v_med3_u32 v83, v83, v86, v17
	v_med3_u32 v84, v86, v87, v17
	v_med3_u32 v85, v87, v88, v17
	v_med3_u32 v86, v88, v89, v17
	v_med3_u32 v87, v89, v80, v17
	v_med3_u32 v80, v80, v90, v17
	v_min_u32_e32 v17, v90, v17
	v_ashrrev_i32_e32 v90, 31, v21
	v_or_b32_e32 v89, 9, v52
	v_bitop3_b32 v21, v90, v21, s18 bitop3:0x36
	v_bitop3_b32 v21, v21, v89, s19 bitop3:0x36
	v_max_u32_e32 v89, v18, v21
	v_min_u32_e32 v18, v18, v21
	v_max_u32_e32 v21, v20, v18
	v_med3_u32 v20, v20, v19, v18
	v_med3_u32 v19, v19, v79, v18
	v_med3_u32 v79, v79, v53, v18
	v_med3_u32 v53, v53, v78, v18
	v_med3_u32 v78, v78, v81, v18
	v_med3_u32 v81, v81, v82, v18
	v_med3_u32 v82, v82, v83, v18
	v_med3_u32 v83, v83, v84, v18
; __device__ __forceinline__ void ins16(u32 (&top)[16], u32 v) {
; #pragma unroll
;   for (int j = 0; j < 16; ++j) {
;     u32 hi = max(top[j], v);
;     v = min(top[j], v);
;     top[j] = hi;
;   }
; }
; __device__ void topk_phase(const Params& p) {
;     ...
;           const u32 kbase = (u32)(kp * 64 + 4 * lh);
; #pragma unroll
;           for (int kt = 0; kt < 2; ++kt)
; #pragma unroll
;             for (int r = 0; r < 16; ++r) {
;               const u32 key = (u32)(kt * 32 + (r & 3) + 8 * (r >> 2)) + kbase;
;               const u32 v = (ord_enc(acc[kt][r]) | 127u) ^ key;
;               ins16(top, v);
;             }
	v_med3_u32 v84, v84, v85, v18
	v_med3_u32 v85, v85, v86, v18
	v_med3_u32 v86, v86, v87, v18
	v_max_u32_e32 v88, v91, v17
	v_med3_u32 v87, v87, v80, v18
	v_min_u32_e32 v17, v91, v17
	v_med3_u32 v80, v80, v88, v18
	v_min_u32_e32 v18, v88, v18
	v_max3_u32 v16, v16, v17, v18
	v_ashrrev_i32_e32 v18, 31, v22
	v_or_b32_e32 v17, 10, v52
	v_bitop3_b32 v18, v18, v22, s18 bitop3:0x36
	v_bitop3_b32 v17, v18, v17, s19 bitop3:0x36
	v_max_u32_e32 v18, v89, v17
	v_min_u32_e32 v17, v89, v17
	v_max_u32_e32 v22, v21, v17
	v_med3_u32 v21, v21, v20, v17
	v_med3_u32 v20, v20, v19, v17
	v_med3_u32 v19, v19, v79, v17
	v_med3_u32 v79, v79, v53, v17
	v_med3_u32 v53, v53, v78, v17
	v_med3_u32 v78, v78, v81, v17
	v_med3_u32 v81, v81, v82, v17
	v_med3_u32 v82, v82, v83, v17
	v_med3_u32 v83, v83, v84, v17
	v_med3_u32 v84, v84, v85, v17
	v_med3_u32 v85, v85, v86, v17
	v_med3_u32 v86, v86, v87, v17
	v_ashrrev_i32_e32 v88, 31, v23
	v_med3_u32 v87, v87, v80, v17
	v_min_u32_e32 v17, v80, v17
	v_or_b32_e32 v80, 11, v52
	v_bitop3_b32 v23, v88, v23, s18 bitop3:0x36
	v_bitop3_b32 v23, v23, v80, s19 bitop3:0x36
	v_max_u32_e32 v80, v18, v23
	v_min_u32_e32 v18, v18, v23
	v_max_u32_e32 v23, v22, v18
	v_med3_u32 v22, v22, v21, v18
	v_med3_u32 v21, v21, v20, v18
	v_med3_u32 v20, v20, v19, v18
	v_med3_u32 v19, v19, v79, v18
	v_med3_u32 v79, v79, v53, v18
	v_med3_u32 v53, v53, v78, v18
	v_med3_u32 v78, v78, v81, v18
	v_med3_u32 v81, v81, v82, v18
	v_med3_u32 v82, v82, v83, v18
	v_med3_u32 v83, v83, v84, v18
	v_med3_u32 v84, v84, v85, v18
	v_med3_u32 v85, v85, v86, v18
	v_med3_u32 v86, v86, v87, v18
	v_min_u32_e32 v18, v87, v18
	v_max3_u32 v16, v16, v17, v18
	v_ashrrev_i32_e32 v18, 31, v24
	v_or_b32_e32 v17, 16, v52
	v_bitop3_b32 v18, v18, v24, s18 bitop3:0x36
	v_bitop3_b32 v17, v18, v17, s19 bitop3:0x36
	v_max_u32_e32 v18, v80, v17
	v_min_u32_e32 v17, v80, v17
	v_max_u32_e32 v24, v23, v17
	v_med3_u32 v23, v23, v22, v17
	v_med3_u32 v22, v22, v21, v17
	v_med3_u32 v21, v21, v20, v17
	v_med3_u32 v20, v20, v19, v17
	v_med3_u32 v19, v19, v79, v17
	v_med3_u32 v79, v79, v53, v17
	v_med3_u32 v53, v53, v78, v17
	v_med3_u32 v78, v78, v81, v17
	v_med3_u32 v80, v81, v82, v17
	v_med3_u32 v81, v82, v83, v17
	v_med3_u32 v82, v83, v84, v17
	v_med3_u32 v83, v84, v85, v17
	v_med3_u32 v84, v85, v86, v17
	v_min_u32_e32 v17, v86, v17
	v_ashrrev_i32_e32 v86, 31, v25
	v_or_b32_e32 v85, 17, v52
	v_bitop3_b32 v25, v86, v25, s18 bitop3:0x36
	v_bitop3_b32 v25, v25, v85, s19 bitop3:0x36
	v_max_u32_e32 v85, v18, v25
	v_min_u32_e32 v18, v18, v25
	v_max_u32_e32 v25, v24, v18
	v_med3_u32 v24, v24, v23, v18
	v_med3_u32 v23, v23, v22, v18
	v_med3_u32 v22, v22, v21, v18
	v_med3_u32 v21, v21, v20, v18
	v_med3_u32 v20, v20, v19, v18
	v_med3_u32 v19, v19, v79, v18
	v_med3_u32 v79, v79, v53, v18
	v_med3_u32 v53, v53, v78, v18
	v_med3_u32 v78, v78, v80, v18
	v_med3_u32 v80, v80, v81, v18
	v_med3_u32 v81, v81, v82, v18
	v_med3_u32 v82, v82, v83, v18
	v_med3_u32 v83, v83, v84, v18
	v_min_u32_e32 v18, v84, v18
	v_max3_u32 v16, v16, v17, v18
	v_ashrrev_i32_e32 v18, 31, v26
	v_or_b32_e32 v17, 18, v52
	v_bitop3_b32 v18, v18, v26, s18 bitop3:0x36
	v_bitop3_b32 v17, v18, v17, s19 bitop3:0x36
	v_max_u32_e32 v18, v85, v17
	v_min_u32_e32 v17, v85, v17
	v_max_u32_e32 v26, v25, v17
	v_med3_u32 v25, v25, v24, v17
	v_med3_u32 v24, v24, v23, v17
	v_med3_u32 v23, v23, v22, v17
	v_med3_u32 v22, v22, v21, v17
	v_med3_u32 v21, v21, v20, v17
	v_med3_u32 v20, v20, v19, v17
	v_med3_u32 v19, v19, v79, v17
	v_med3_u32 v79, v79, v53, v17
	v_med3_u32 v53, v53, v78, v17
	v_med3_u32 v78, v78, v80, v17
	v_med3_u32 v80, v80, v81, v17
	v_med3_u32 v81, v81, v82, v17
	v_ashrrev_i32_e32 v84, 31, v27
	v_med3_u32 v82, v82, v83, v17
	v_min_u32_e32 v17, v83, v17
	v_or_b32_e32 v83, 19, v52
	v_bitop3_b32 v27, v84, v27, s18 bitop3:0x36
	v_bitop3_b32 v27, v27, v83, s19 bitop3:0x36
	v_max_u32_e32 v83, v18, v27
	v_min_u32_e32 v18, v18, v27
	v_max_u32_e32 v27, v26, v18
	v_med3_u32 v26, v26, v25, v18
	v_med3_u32 v25, v25, v24, v18
	v_med3_u32 v24, v24, v23, v18
	v_med3_u32 v23, v23, v22, v18
	v_med3_u32 v22, v22, v21, v18
	v_med3_u32 v21, v21, v20, v18
	v_med3_u32 v20, v20, v19, v18
	v_med3_u32 v19, v19, v79, v18
	v_med3_u32 v79, v79, v53, v18
	v_med3_u32 v53, v53, v78, v18
	v_med3_u32 v78, v78, v80, v18
	v_med3_u32 v80, v80, v81, v18
	v_med3_u32 v81, v81, v82, v18
	v_min_u32_e32 v18, v82, v18
	v_max3_u32 v16, v16, v17, v18
	v_ashrrev_i32_e32 v18, 31, v28
	v_or_b32_e32 v17, 24, v52
	v_bitop3_b32 v18, v18, v28, s18 bitop3:0x36
	v_bitop3_b32 v17, v18, v17, s19 bitop3:0x36
	v_max_u32_e32 v18, v83, v17
	v_min_u32_e32 v17, v83, v17
	v_max_u32_e32 v28, v27, v17
	v_med3_u32 v27, v27, v26, v17
	v_med3_u32 v26, v26, v25, v17
	v_med3_u32 v25, v25, v24, v17
	v_med3_u32 v24, v24, v23, v17
	v_med3_u32 v23, v23, v22, v17
	v_med3_u32 v22, v22, v21, v17
	v_med3_u32 v21, v21, v20, v17
	v_med3_u32 v20, v20, v19, v17
	v_med3_u32 v19, v19, v79, v17
	v_med3_u32 v79, v79, v53, v17
	v_med3_u32 v53, v53, v78, v17
	v_med3_u32 v78, v78, v80, v17
	v_ashrrev_i32_e32 v82, 31, v29
	v_med3_u32 v80, v80, v81, v17
	v_min_u32_e32 v17, v81, v17
	v_or_b32_e32 v81, 25, v52
	v_bitop3_b32 v29, v82, v29, s18 bitop3:0x36
	v_bitop3_b32 v29, v29, v81, s19 bitop3:0x36
	v_max_u32_e32 v81, v18, v29
	v_min_u32_e32 v18, v18, v29
	v_max_u32_e32 v29, v28, v18
	v_med3_u32 v28, v28, v27, v18
	v_med3_u32 v27, v27, v26, v18
	v_med3_u32 v26, v26, v25, v18
	v_med3_u32 v25, v25, v24, v18
	v_med3_u32 v24, v24, v23, v18
	v_med3_u32 v23, v23, v22, v18
	v_med3_u32 v22, v22, v21, v18
	v_med3_u32 v21, v21, v20, v18
	v_med3_u32 v20, v20, v19, v18
	v_med3_u32 v19, v19, v79, v18
	v_med3_u32 v79, v79, v53, v18
	v_med3_u32 v53, v53, v78, v18
; __device__ __forceinline__ void ins16(u32 (&top)[16], u32 v) {
; #pragma unroll
;   for (int j = 0; j < 16; ++j) {
;     u32 hi = max(top[j], v);
;     v = min(top[j], v);
;     top[j] = hi;
;   }
; }
; __device__ void topk_phase(const Params& p) {
;     ...
;           const u32 kbase = (u32)(kp * 64 + 4 * lh);
; #pragma unroll
;           for (int kt = 0; kt < 2; ++kt)
; #pragma unroll
;             for (int r = 0; r < 16; ++r) {
;               const u32 key = (u32)(kt * 32 + (r & 3) + 8 * (r >> 2)) + kbase;
;               const u32 v = (ord_enc(acc[kt][r]) | 127u) ^ key;
;               ins16(top, v);
;             }
	v_med3_u32 v78, v78, v80, v18
	v_min_u32_e32 v18, v80, v18
	v_max3_u32 v16, v16, v17, v18
	v_ashrrev_i32_e32 v18, 31, v30
	v_or_b32_e32 v17, 26, v52
	v_bitop3_b32 v18, v18, v30, s18 bitop3:0x36
	v_bitop3_b32 v17, v18, v17, s19 bitop3:0x36
	v_max_u32_e32 v18, v81, v17
	v_min_u32_e32 v17, v81, v17
	v_max_u32_e32 v30, v29, v17
	v_med3_u32 v29, v29, v28, v17
	v_med3_u32 v28, v28, v27, v17
	v_med3_u32 v27, v27, v26, v17
	v_med3_u32 v26, v26, v25, v17
	v_med3_u32 v25, v25, v24, v17
	v_med3_u32 v24, v24, v23, v17
	v_med3_u32 v23, v23, v22, v17
	v_med3_u32 v22, v22, v21, v17
	v_med3_u32 v21, v21, v20, v17
	v_med3_u32 v20, v20, v19, v17
	v_med3_u32 v19, v19, v79, v17
	v_med3_u32 v79, v79, v53, v17
	v_ashrrev_i32_e32 v80, 31, v31
	v_med3_u32 v53, v53, v78, v17
	v_min_u32_e32 v17, v78, v17
	v_or_b32_e32 v78, 27, v52
	v_bitop3_b32 v31, v80, v31, s18 bitop3:0x36
	v_bitop3_b32 v31, v31, v78, s19 bitop3:0x36
	v_max_u32_e32 v78, v18, v31
	v_min_u32_e32 v18, v18, v31
	v_max_u32_e32 v31, v30, v18
	v_med3_u32 v30, v30, v29, v18
	v_med3_u32 v29, v29, v28, v18
	v_med3_u32 v28, v28, v27, v18
	v_med3_u32 v27, v27, v26, v18
	v_med3_u32 v26, v26, v25, v18
	v_med3_u32 v25, v25, v24, v18
	v_med3_u32 v24, v24, v23, v18
	v_med3_u32 v23, v23, v22, v18
	v_med3_u32 v22, v22, v21, v18
	v_med3_u32 v21, v21, v20, v18
	v_med3_u32 v20, v20, v19, v18
	v_med3_u32 v19, v19, v79, v18
	v_med3_u32 v79, v79, v53, v18
	v_min_u32_e32 v18, v53, v18
	v_max3_u32 v16, v16, v17, v18
	v_ashrrev_i32_e32 v18, 31, v0
	v_or_b32_e32 v17, 32, v52
	v_bitop3_b32 v0, v18, v0, s18 bitop3:0x36
	v_bitop3_b32 v0, v0, v17, s19 bitop3:0x36
	v_max_u32_e32 v17, v78, v0
	v_min_u32_e32 v0, v78, v0
	v_ashrrev_i32_e32 v78, 31, v1
	v_or_b32_e32 v53, 33, v52
	v_bitop3_b32 v1, v78, v1, s18 bitop3:0x36
	v_bitop3_b32 v1, v1, v53, s19 bitop3:0x36
	v_max_u32_e32 v18, v31, v0
	v_min_u32_e32 v0, v31, v0
	v_max_u32_e32 v53, v17, v1
	v_min_u32_e32 v1, v17, v1
	v_max_u32_e32 v31, v30, v0
	v_min_u32_e32 v0, v30, v0
	v_max_u32_e32 v17, v18, v1
	v_min_u32_e32 v1, v18, v1
	v_max_u32_e32 v30, v29, v0
	v_min_u32_e32 v0, v29, v0
	v_max_u32_e32 v18, v31, v1
	v_min_u32_e32 v1, v31, v1
	v_max_u32_e32 v29, v28, v0
	v_min_u32_e32 v0, v28, v0
	v_max_u32_e32 v31, v30, v1
	v_min_u32_e32 v1, v30, v1
	v_max_u32_e32 v28, v27, v0
	v_min_u32_e32 v0, v27, v0
	v_max_u32_e32 v30, v29, v1
	v_min_u32_e32 v1, v29, v1
	v_max_u32_e32 v27, v26, v0
	v_min_u32_e32 v0, v26, v0
	v_max_u32_e32 v29, v28, v1
	v_min_u32_e32 v1, v28, v1
	v_max_u32_e32 v26, v25, v0
	v_min_u32_e32 v0, v25, v0
	v_max_u32_e32 v28, v27, v1
	v_min_u32_e32 v1, v27, v1
	v_max_u32_e32 v25, v24, v0
	v_min_u32_e32 v0, v24, v0
	v_max_u32_e32 v27, v26, v1
	v_min_u32_e32 v1, v26, v1
	v_max_u32_e32 v24, v23, v0
	v_min_u32_e32 v0, v23, v0
	v_max_u32_e32 v26, v25, v1
	v_min_u32_e32 v1, v25, v1
	v_max_u32_e32 v23, v22, v0
	v_min_u32_e32 v0, v22, v0
	v_max_u32_e32 v25, v24, v1
	v_min_u32_e32 v1, v24, v1
	v_max_u32_e32 v22, v21, v0
	v_min_u32_e32 v0, v21, v0
	v_max_u32_e32 v24, v23, v1
	v_min_u32_e32 v1, v23, v1
	v_max_u32_e32 v21, v20, v0
	v_min_u32_e32 v0, v20, v0
	v_max_u32_e32 v23, v22, v1
	v_min_u32_e32 v1, v22, v1
	v_max_u32_e32 v20, v19, v0
	v_min_u32_e32 v0, v19, v0
	v_max_u32_e32 v22, v21, v1
	v_min_u32_e32 v1, v21, v1
	v_max_u32_e32 v19, v79, v0
	v_max_u32_e32 v21, v20, v1
	v_min_u32_e32 v1, v20, v1
	v_min_u32_e32 v0, v79, v0
	v_max_u32_e32 v20, v19, v1
	v_min_u32_e32 v1, v19, v1
	v_max3_u32 v0, v16, v0, v1
	v_ashrrev_i32_e32 v16, 31, v2
	v_or_b32_e32 v1, 34, v52
	v_bitop3_b32 v2, v16, v2, s18 bitop3:0x36
	v_bitop3_b32 v1, v2, v1, s19 bitop3:0x36
	v_max_u32_e32 v2, v53, v1
	v_min_u32_e32 v1, v53, v1
	v_max_u32_e32 v16, v17, v1
	v_med3_u32 v17, v17, v18, v1
	v_med3_u32 v18, v18, v31, v1
	v_med3_u32 v19, v31, v30, v1
	v_med3_u32 v30, v30, v29, v1
	v_med3_u32 v29, v29, v28, v1
	v_med3_u32 v28, v28, v27, v1
	v_med3_u32 v27, v27, v26, v1
	v_med3_u32 v26, v26, v25, v1
	v_med3_u32 v25, v25, v24, v1
	v_med3_u32 v24, v24, v23, v1
	v_med3_u32 v23, v23, v22, v1
	v_med3_u32 v22, v22, v21, v1
	v_ashrrev_i32_e32 v31, 31, v3
	v_med3_u32 v21, v21, v20, v1
	v_min_u32_e32 v1, v20, v1
	v_or_b32_e32 v20, 35, v52
	v_bitop3_b32 v3, v31, v3, s18 bitop3:0x36
	v_bitop3_b32 v3, v3, v20, s19 bitop3:0x36
	v_max_u32_e32 v20, v2, v3
	v_min_u32_e32 v2, v2, v3
	v_max_u32_e32 v3, v16, v2
	v_med3_u32 v16, v16, v17, v2
	v_med3_u32 v17, v17, v18, v2
	v_med3_u32 v18, v18, v19, v2
	v_med3_u32 v19, v19, v30, v2
	v_med3_u32 v30, v30, v29, v2
	v_med3_u32 v29, v29, v28, v2
	v_med3_u32 v28, v28, v27, v2
	v_med3_u32 v27, v27, v26, v2
	v_med3_u32 v26, v26, v25, v2
	v_med3_u32 v25, v25, v24, v2
	v_med3_u32 v24, v24, v23, v2
	v_med3_u32 v23, v23, v22, v2
	v_med3_u32 v22, v22, v21, v2
	v_min_u32_e32 v2, v21, v2
	v_max3_u32 v0, v0, v1, v2
	v_ashrrev_i32_e32 v2, 31, v4
	v_or_b32_e32 v1, 40, v52
	v_bitop3_b32 v2, v2, v4, s18 bitop3:0x36
	v_bitop3_b32 v1, v2, v1, s19 bitop3:0x36
	v_max_u32_e32 v2, v20, v1
	v_min_u32_e32 v1, v20, v1
	v_max_u32_e32 v4, v3, v1
	v_med3_u32 v3, v3, v16, v1
	v_med3_u32 v16, v16, v17, v1
	v_med3_u32 v17, v17, v18, v1
	v_med3_u32 v18, v18, v19, v1
	v_med3_u32 v19, v19, v30, v1
	v_med3_u32 v20, v30, v29, v1
	v_med3_u32 v21, v29, v28, v1
	v_med3_u32 v28, v28, v27, v1
	v_med3_u32 v27, v27, v26, v1
	v_med3_u32 v26, v26, v25, v1
	v_med3_u32 v25, v25, v24, v1
	v_med3_u32 v24, v24, v23, v1
	v_ashrrev_i32_e32 v29, 31, v5
	v_med3_u32 v23, v23, v22, v1
	v_min_u32_e32 v1, v22, v1
	v_or_b32_e32 v22, 41, v52
	v_bitop3_b32 v5, v29, v5, s18 bitop3:0x36
	v_bitop3_b32 v5, v5, v22, s19 bitop3:0x36
	v_max_u32_e32 v22, v2, v5
	v_min_u32_e32 v2, v2, v5
	v_max_u32_e32 v5, v4, v2
	v_med3_u32 v4, v4, v3, v2
	v_med3_u32 v3, v3, v16, v2
; __device__ __forceinline__ void ins16(u32 (&top)[16], u32 v) {
; #pragma unroll
;   for (int j = 0; j < 16; ++j) {
;     u32 hi = max(top[j], v);
;     v = min(top[j], v);
;     top[j] = hi;
;   }
; }
; __device__ void topk_phase(const Params& p) {
;     ...
;           const u32 kbase = (u32)(kp * 64 + 4 * lh);
; #pragma unroll
;           for (int kt = 0; kt < 2; ++kt)
; #pragma unroll
;             for (int r = 0; r < 16; ++r) {
;               const u32 key = (u32)(kt * 32 + (r & 3) + 8 * (r >> 2)) + kbase;
;               const u32 v = (ord_enc(acc[kt][r]) | 127u) ^ key;
;               ins16(top, v);
;             }
	v_med3_u32 v16, v16, v17, v2
	v_med3_u32 v17, v17, v18, v2
	v_med3_u32 v18, v18, v19, v2
	v_med3_u32 v19, v19, v20, v2
	v_med3_u32 v20, v20, v21, v2
	v_med3_u32 v21, v21, v28, v2
	v_med3_u32 v28, v28, v27, v2
	v_med3_u32 v27, v27, v26, v2
	v_med3_u32 v26, v26, v25, v2
	v_med3_u32 v25, v25, v24, v2
	v_med3_u32 v24, v24, v23, v2
	v_min_u32_e32 v2, v23, v2
	v_max3_u32 v0, v0, v1, v2
	v_ashrrev_i32_e32 v2, 31, v6
	v_or_b32_e32 v1, 42, v52
	v_bitop3_b32 v2, v2, v6, s18 bitop3:0x36
	v_bitop3_b32 v1, v2, v1, s19 bitop3:0x36
	v_max_u32_e32 v2, v22, v1
	v_min_u32_e32 v1, v22, v1
	v_max_u32_e32 v6, v5, v1
	v_med3_u32 v5, v5, v4, v1
	v_med3_u32 v4, v4, v3, v1
	v_med3_u32 v3, v3, v16, v1
	v_med3_u32 v16, v16, v17, v1
	v_med3_u32 v17, v17, v18, v1
	v_med3_u32 v18, v18, v19, v1
	v_med3_u32 v19, v19, v20, v1
	v_med3_u32 v20, v20, v21, v1
	v_med3_u32 v21, v21, v28, v1
	v_med3_u32 v22, v28, v27, v1
	v_med3_u32 v23, v27, v26, v1
	v_med3_u32 v26, v26, v25, v1
	v_ashrrev_i32_e32 v27, 31, v7
	v_med3_u32 v25, v25, v24, v1
	v_min_u32_e32 v1, v24, v1
	v_or_b32_e32 v24, 43, v52
	v_bitop3_b32 v7, v27, v7, s18 bitop3:0x36
	v_bitop3_b32 v7, v7, v24, s19 bitop3:0x36
	v_max_u32_e32 v24, v2, v7
	v_min_u32_e32 v2, v2, v7
	v_max_u32_e32 v7, v6, v2
	v_med3_u32 v6, v6, v5, v2
	v_med3_u32 v5, v5, v4, v2
	v_med3_u32 v4, v4, v3, v2
	v_med3_u32 v3, v3, v16, v2
	v_med3_u32 v16, v16, v17, v2
	v_med3_u32 v17, v17, v18, v2
	v_med3_u32 v18, v18, v19, v2
	v_med3_u32 v19, v19, v20, v2
	v_med3_u32 v20, v20, v21, v2
	v_med3_u32 v21, v21, v22, v2
	v_med3_u32 v22, v22, v23, v2
	v_med3_u32 v23, v23, v26, v2
	v_med3_u32 v26, v26, v25, v2
	v_min_u32_e32 v2, v25, v2
	v_max3_u32 v0, v0, v1, v2
	v_ashrrev_i32_e32 v2, 31, v8
	v_or_b32_e32 v1, 48, v52
	v_bitop3_b32 v2, v2, v8, s18 bitop3:0x36
	v_bitop3_b32 v1, v2, v1, s19 bitop3:0x36
	v_ashrrev_i32_e32 v25, 31, v9
	v_max_u32_e32 v2, v24, v1
	v_min_u32_e32 v1, v24, v1
	v_or_b32_e32 v24, 49, v52
	v_bitop3_b32 v9, v25, v9, s18 bitop3:0x36
	v_bitop3_b32 v9, v9, v24, s19 bitop3:0x36
	v_max_u32_e32 v8, v7, v1
	v_min_u32_e32 v1, v7, v1
	v_max_u32_e32 v24, v2, v9
	v_min_u32_e32 v2, v2, v9
	v_max_u32_e32 v7, v6, v1
	v_min_u32_e32 v1, v6, v1
	v_max_u32_e32 v9, v8, v2
	v_min_u32_e32 v2, v8, v2
	v_max_u32_e32 v6, v5, v1
	v_min_u32_e32 v1, v5, v1
	v_max_u32_e32 v8, v7, v2
	v_min_u32_e32 v2, v7, v2
	v_max_u32_e32 v5, v4, v1
	v_min_u32_e32 v1, v4, v1
	v_max_u32_e32 v7, v6, v2
	v_min_u32_e32 v2, v6, v2
	v_max_u32_e32 v4, v3, v1
	v_min_u32_e32 v1, v3, v1
	v_max_u32_e32 v6, v5, v2
	v_min_u32_e32 v2, v5, v2
	v_max_u32_e32 v3, v16, v1
	v_min_u32_e32 v1, v16, v1
	v_max_u32_e32 v5, v4, v2
	v_min_u32_e32 v2, v4, v2
	v_max_u32_e32 v16, v17, v1
	v_min_u32_e32 v1, v17, v1
	v_max_u32_e32 v4, v3, v2
	v_min_u32_e32 v2, v3, v2
	v_max_u32_e32 v17, v18, v1
	v_min_u32_e32 v1, v18, v1
	v_max_u32_e32 v3, v16, v2
	v_min_u32_e32 v2, v16, v2
	v_max_u32_e32 v18, v19, v1
	v_min_u32_e32 v1, v19, v1
	v_max_u32_e32 v16, v17, v2
	v_min_u32_e32 v2, v17, v2
	v_max_u32_e32 v19, v20, v1
	v_min_u32_e32 v1, v20, v1
	v_max_u32_e32 v17, v18, v2
	v_min_u32_e32 v2, v18, v2
	v_max_u32_e32 v20, v21, v1
	v_min_u32_e32 v1, v21, v1
	v_max_u32_e32 v18, v19, v2
	v_min_u32_e32 v2, v19, v2
	v_max_u32_e32 v21, v22, v1
	v_min_u32_e32 v1, v22, v1
	v_max_u32_e32 v19, v20, v2
	v_min_u32_e32 v2, v20, v2
	v_max_u32_e32 v22, v23, v1
	v_min_u32_e32 v1, v23, v1
	v_max_u32_e32 v20, v21, v2
	v_min_u32_e32 v2, v21, v2
	v_max_u32_e32 v23, v26, v1
	v_max_u32_e32 v21, v22, v2
	v_min_u32_e32 v2, v22, v2
	v_min_u32_e32 v1, v26, v1
	v_max_u32_e32 v22, v23, v2
	v_min_u32_e32 v2, v23, v2
	v_max3_u32 v0, v0, v1, v2
	v_ashrrev_i32_e32 v2, 31, v10
	v_or_b32_e32 v1, 50, v52
	v_bitop3_b32 v2, v2, v10, s18 bitop3:0x36
	v_bitop3_b32 v1, v2, v1, s19 bitop3:0x36
	v_max_u32_e32 v2, v24, v1
	v_min_u32_e32 v1, v24, v1
	v_max_u32_e32 v10, v9, v1
	v_med3_u32 v9, v9, v8, v1
	v_med3_u32 v8, v8, v7, v1
	v_med3_u32 v7, v7, v6, v1
	v_med3_u32 v6, v6, v5, v1
	v_med3_u32 v5, v5, v4, v1
	v_med3_u32 v4, v4, v3, v1
	v_med3_u32 v3, v3, v16, v1
	v_med3_u32 v16, v16, v17, v1
	v_med3_u32 v17, v17, v18, v1
	v_med3_u32 v18, v18, v19, v1
	v_med3_u32 v19, v19, v20, v1
	v_med3_u32 v20, v20, v21, v1
	v_ashrrev_i32_e32 v23, 31, v11
	v_med3_u32 v21, v21, v22, v1
	v_min_u32_e32 v1, v22, v1
	v_or_b32_e32 v22, 51, v52
	v_bitop3_b32 v11, v23, v11, s18 bitop3:0x36
	v_bitop3_b32 v11, v11, v22, s19 bitop3:0x36
	v_max_u32_e32 v22, v2, v11
	v_min_u32_e32 v2, v2, v11
	v_max_u32_e32 v11, v10, v2
	v_med3_u32 v10, v10, v9, v2
	v_med3_u32 v9, v9, v8, v2
	v_med3_u32 v8, v8, v7, v2
	v_med3_u32 v7, v7, v6, v2
	v_med3_u32 v6, v6, v5, v2
	v_med3_u32 v5, v5, v4, v2
	v_med3_u32 v4, v4, v3, v2
	v_med3_u32 v3, v3, v16, v2
	v_med3_u32 v16, v16, v17, v2
	v_med3_u32 v17, v17, v18, v2
	v_med3_u32 v18, v18, v19, v2
	v_med3_u32 v19, v19, v20, v2
	v_med3_u32 v20, v20, v21, v2
	v_min_u32_e32 v2, v21, v2
	v_max3_u32 v0, v0, v1, v2
	v_ashrrev_i32_e32 v2, 31, v12
	v_or_b32_e32 v1, 56, v52
	v_bitop3_b32 v2, v2, v12, s18 bitop3:0x36
	v_bitop3_b32 v1, v2, v1, s19 bitop3:0x36
	v_max_u32_e32 v2, v22, v1
	v_min_u32_e32 v1, v22, v1
	v_max_u32_e32 v12, v11, v1
	v_med3_u32 v11, v11, v10, v1
	v_med3_u32 v10, v10, v9, v1
	v_med3_u32 v9, v9, v8, v1
	v_med3_u32 v8, v8, v7, v1
	v_med3_u32 v7, v7, v6, v1
	v_med3_u32 v6, v6, v5, v1
	v_med3_u32 v5, v5, v4, v1
	v_med3_u32 v4, v4, v3, v1
	v_med3_u32 v3, v3, v16, v1
	v_med3_u32 v16, v16, v17, v1
	v_med3_u32 v17, v17, v18, v1
	v_med3_u32 v18, v18, v19, v1
	v_ashrrev_i32_e32 v21, 31, v13
	v_med3_u32 v19, v19, v20, v1
	v_min_u32_e32 v1, v20, v1
	v_or_b32_e32 v20, 57, v52
	v_bitop3_b32 v13, v21, v13, s18 bitop3:0x36
	v_bitop3_b32 v13, v13, v20, s19 bitop3:0x36
; __device__ void topk_phase(const Params& p) {
;     ...
;           const u32 kbase = (u32)(kp * 64 + 4 * lh);
; #pragma unroll
;           for (int kt = 0; kt < 2; ++kt)
; #pragma unroll
;             for (int r = 0; r < 16; ++r) {
;               const u32 key = (u32)(kt * 32 + (r & 3) + 8 * (r >> 2)) + kbase;
;               const u32 v = (ord_enc(acc[kt][r]) | 127u) ^ key;
;               ins16(top, v);
;             }
;         }
;         u32 mg[16];
; #pragma unroll
;         for (int j = 0; j < 16; ++j) {
;           u32 o = (u32)__shfl_xor((int)top[15 - j], 32);
;           mg[j] = max(top[j], o);
;         }
; #pragma unroll
;         for (int st = 8; st >= 1; st >>= 1)
; #pragma unroll
;           for (int i = 0; i < 16; ++i)
;             if ((i & st) == 0) {
;               u32 hi = max(mg[i], mg[i + st]), lo = min(mg[i], mg[i + st]);
;               mg[i] = hi; mg[i + st] = lo;
;             }
	v_max_u32_e32 v20, v2, v13
	v_min_u32_e32 v2, v2, v13
	v_max_u32_e32 v13, v12, v2
	v_med3_u32 v12, v12, v11, v2
	v_med3_u32 v11, v11, v10, v2
	v_med3_u32 v10, v10, v9, v2
	v_med3_u32 v9, v9, v8, v2
	v_med3_u32 v8, v8, v7, v2
	v_med3_u32 v7, v7, v6, v2
	v_med3_u32 v6, v6, v5, v2
	v_med3_u32 v5, v5, v4, v2
	v_med3_u32 v4, v4, v3, v2
	v_med3_u32 v3, v3, v16, v2
	v_med3_u32 v16, v16, v17, v2
	v_med3_u32 v17, v17, v18, v2
	v_med3_u32 v18, v18, v19, v2
	v_min_u32_e32 v2, v19, v2
	v_max3_u32 v0, v0, v1, v2
	v_ashrrev_i32_e32 v2, 31, v14
	v_or_b32_e32 v1, 58, v52
	v_bitop3_b32 v2, v2, v14, s18 bitop3:0x36
	v_bitop3_b32 v1, v2, v1, s19 bitop3:0x36
	v_max_u32_e32 v2, v20, v1
	v_min_u32_e32 v1, v20, v1
	v_max_u32_e32 v14, v13, v1
	v_med3_u32 v13, v13, v12, v1
	v_med3_u32 v12, v12, v11, v1
	v_med3_u32 v11, v11, v10, v1
	v_med3_u32 v10, v10, v9, v1
	v_med3_u32 v9, v9, v8, v1
	v_med3_u32 v8, v8, v7, v1
	v_med3_u32 v7, v7, v6, v1
	v_med3_u32 v6, v6, v5, v1
	v_med3_u32 v5, v5, v4, v1
	v_med3_u32 v4, v4, v3, v1
	v_med3_u32 v3, v3, v16, v1
	v_med3_u32 v16, v16, v17, v1
	v_ashrrev_i32_e32 v19, 31, v15
	v_med3_u32 v17, v17, v18, v1
	v_min_u32_e32 v1, v18, v1
	v_or_b32_e32 v18, 59, v52
	v_bitop3_b32 v15, v19, v15, s18 bitop3:0x36
	v_bitop3_b32 v15, v15, v18, s19 bitop3:0x36
	v_max_u32_e32 v78, v2, v15
	v_min_u32_e32 v2, v2, v15
	v_max_u32_e32 v81, v14, v2
	v_med3_u32 v82, v14, v13, v2
	v_med3_u32 v83, v13, v12, v2
	v_med3_u32 v88, v12, v11, v2
	v_med3_u32 v90, v11, v10, v2
	v_med3_u32 v91, v10, v9, v2
	v_med3_u32 v89, v9, v8, v2
	v_med3_u32 v80, v8, v7, v2
	v_med3_u32 v92, v7, v6, v2
	v_med3_u32 v93, v6, v5, v2
	v_med3_u32 v84, v5, v4, v2
	v_med3_u32 v85, v4, v3, v2
	v_med3_u32 v86, v3, v16, v2
	v_med3_u32 v87, v16, v17, v2
	v_min_u32_e32 v2, v17, v2
	s_mov_b32 s4, 1
	v_max3_u32 v79, v0, v1, v2
	s_andn2_b64 vcc, exec, s[10:11]
	s_mov_b64 s[10:11], 0
	s_cbranch_vccnz .LBB0_787
	ds_bpermute_b32 v5, v55, v63
	ds_bpermute_b32 v6, v55, v65
	ds_bpermute_b32 v7, v55, v34
	ds_bpermute_b32 v13, v55, v73
	s_waitcnt lgkmcnt(6)
	v_max_u32_e32 v1, v66, v75
	s_waitcnt lgkmcnt(5)
	v_max_u32_e32 v3, v71, v74
	v_min_u32_e32 v4, v1, v3
	ds_bpermute_b32 v9, v55, v61
	v_max_u32_e32 v1, v1, v3
	s_waitcnt lgkmcnt(3)
	v_max_u32_e32 v3, v68, v6
	s_waitcnt lgkmcnt(2)
	v_max_u32_e32 v6, v62, v7
	v_max_u32_e32 v5, v69, v5
	ds_bpermute_b32 v0, v55, v64
	v_max_u32_e32 v10, v6, v5
	ds_bpermute_b32 v11, v55, v69
	ds_bpermute_b32 v14, v55, v72
	ds_bpermute_b32 v15, v55, v71
	ds_bpermute_b32 v16, v55, v70
	ds_bpermute_b32 v17, v55, v68
	ds_bpermute_b32 v18, v55, v66
	v_min_u32_e32 v5, v6, v5
	s_waitcnt lgkmcnt(8)
	v_max_u32_e32 v6, v43, v13
	ds_bpermute_b32 v13, v55, v62
	s_waitcnt lgkmcnt(8)
	v_max_u32_e32 v7, v72, v9
	v_max_u32_e32 v2, v73, v76
	s_waitcnt lgkmcnt(7)
	v_max_u32_e32 v0, v70, v0
	v_max_u32_e32 v9, v3, v7
	s_waitcnt lgkmcnt(6)
	v_max_u32_e32 v11, v63, v11
	v_min_u32_e32 v3, v3, v7
	s_waitcnt lgkmcnt(5)
	v_max_u32_e32 v7, v61, v14
	s_waitcnt lgkmcnt(4)
	v_max_u32_e32 v14, v60, v15
	s_waitcnt lgkmcnt(3)
	v_max_u32_e32 v15, v64, v16
	s_waitcnt lgkmcnt(2)
	v_max_u32_e32 v16, v65, v17
	s_waitcnt lgkmcnt(1)
	v_max_u32_e32 v17, v67, v18
	s_waitcnt lgkmcnt(0)
	v_max_u32_e32 v13, v34, v13
	v_min_u32_e32 v8, v0, v2
	v_max_u32_e32 v0, v0, v2
	v_max_u32_e32 v18, v11, v13
	v_max_u32_e32 v21, v6, v15
	v_max_u32_e32 v22, v7, v16
	v_max_u32_e32 v23, v14, v17
	v_min_u32_e32 v11, v11, v13
	v_min_u32_e32 v13, v6, v15
	v_min_u32_e32 v7, v7, v16
	v_min_u32_e32 v14, v14, v17
	v_max_u32_e32 v2, v1, v0
	v_max_u32_e32 v12, v4, v8
	v_max_u32_e32 v19, v9, v10
	v_max_u32_e32 v24, v18, v22
	v_max_u32_e32 v25, v21, v23
	v_max_u32_e32 v26, v3, v5
	v_min_u32_e32 v15, v18, v22
	v_min_u32_e32 v16, v21, v23
	v_max_u32_e32 v17, v11, v7
	v_max_u32_e32 v18, v13, v14
	v_min_u32_e32 v23, v11, v7
	v_min_u32_e32 v13, v13, v14
	v_min_u32_e32 v0, v1, v0
	v_min_u32_e32 v1, v9, v10
	v_min_u32_e32 v4, v4, v8
	v_min_u32_e32 v3, v3, v5
	v_max_u32_e32 v20, v2, v19
	v_max_u32_e32 v27, v12, v26
	v_max_u32_e32 v21, v24, v25
	v_max_u32_e32 v22, v15, v16
	v_max_u32_e32 v28, v17, v18
	v_max_u32_e32 v29, v23, v13
	v_max_u32_e32 v5, v0, v1
	v_max_u32_e32 v30, v4, v3
	v_min_u32_e32 v14, v24, v25
	v_min_u32_e32 v2, v2, v19
	v_min_u32_e32 v16, v15, v16
	v_min_u32_e32 v0, v0, v1
	v_min_u32_e32 v1, v17, v18
	v_min_u32_e32 v19, v12, v26
	v_min_u32_e32 v23, v23, v13
	v_min_u32_e32 v3, v4, v3
	v_max_u32_e32 v6, v21, v20
	v_max_u32_e32 v7, v28, v27
	v_max_u32_e32 v8, v22, v5
	v_max_u32_e32 v11, v29, v30
	v_max_u32_e32 v9, v14, v2
	v_max_u32_e32 v12, v16, v0
	v_max_u32_e32 v15, v1, v19
	v_max_u32_e32 v17, v23, v3
	v_min_u32_e32 v10, v21, v20
	v_min_u32_e32 v13, v14, v2
	v_min_u32_e32 v14, v22, v5
	v_min_u32_e32 v16, v16, v0
	v_min_u32_e32 v18, v28, v27
	v_min_u32_e32 v19, v1, v19
	v_min_u32_e32 v20, v29, v30
	v_min_u32_e32 v21, v23, v3
	ds_bpermute_b32 v0, v55, v87
	ds_bpermute_b32 v1, v55, v86
	ds_bpermute_b32 v2, v55, v79
	ds_bpermute_b32 v3, v55, v85
	ds_bpermute_b32 v4, v55, v84
	ds_bpermute_b32 v5, v55, v93
	ds_bpermute_b32 v22, v55, v92
	ds_bpermute_b32 v23, v55, v80
	ds_bpermute_b32 v24, v55, v91
	ds_bpermute_b32 v25, v55, v90
	ds_bpermute_b32 v26, v55, v89
	ds_bpermute_b32 v27, v55, v88
	ds_bpermute_b32 v28, v55, v83
	ds_bpermute_b32 v29, v55, v82
	ds_bpermute_b32 v30, v55, v81
	ds_bpermute_b32 v31, v55, v78
	s_waitcnt lgkmcnt(14)
	v_max_u32_e32 v0, v81, v0
	v_max_u32_e32 v1, v82, v1
	s_waitcnt lgkmcnt(12)
	v_max_u32_e32 v3, v83, v3
	s_waitcnt lgkmcnt(11)
	v_max_u32_e32 v4, v88, v4
	s_waitcnt lgkmcnt(10)
	v_max_u32_e32 v5, v90, v5
	s_waitcnt lgkmcnt(9)
	v_max_u32_e32 v22, v91, v22
	s_waitcnt lgkmcnt(8)
	v_max_u32_e32 v23, v89, v23
	s_waitcnt lgkmcnt(7)
; __device__ void topk_phase(const Params& p) {
;     ...
;         for (int st = 8; st >= 1; st >>= 1)
; #pragma unroll
;           for (int i = 0; i < 16; ++i)
;             if ((i & st) == 0) {
;               u32 hi = max(mg[i], mg[i + st]), lo = min(mg[i], mg[i + st]);
;               mg[i] = hi; mg[i + st] = lo;
;             }
; #pragma unroll
;         for (int j = 0; j < 16; ++j) lists[c][j] = mg[j];
;       }
;       float sa[16], sb[16];
; #pragma unroll
;       for (int j = 0; j < 16; ++j) { sa[j] = ord_dec(lists[0][j] & ~127u); sb[j] = ord_dec(lists[1][j] & ~127u); }
;       u32 top[16];
; #pragma unroll
;       for (int j = 0; j < 16; ++j) top[j] = 0u;
; #pragma unroll
;       for (int i = 0; i < 16; ++i)
; #pragma unroll
;         for (int j = 0; j < 16; ++j)
;           if ((i + 1) * (j + 1) <= 16) {
;             const u32 v = (ord_enc(sa[i] + sb[j]) | 255u) ^ (u32)(i * 16 + j);
;             ins16(top, v);
;           }
	v_max_u32_e32 v24, v92, v24
	s_waitcnt lgkmcnt(6)
	v_max_u32_e32 v25, v93, v25
	s_waitcnt lgkmcnt(4)
	v_max_u32_e32 v27, v84, v27
	s_waitcnt lgkmcnt(3)
	v_max_u32_e32 v28, v85, v28
	s_waitcnt lgkmcnt(2)
	v_max_u32_e32 v29, v86, v29
	s_waitcnt lgkmcnt(1)
	v_max_u32_e32 v30, v87, v30
	s_waitcnt lgkmcnt(0)
	v_max_u32_e32 v31, v79, v31
	v_max_u32_e32 v26, v80, v26
	v_max_u32_e32 v2, v78, v2
	v_max_u32_e32 v34, v2, v26
	v_min_u32_e32 v2, v2, v26
	v_max_u32_e32 v26, v0, v24
	v_min_u32_e32 v0, v0, v24
	v_max_u32_e32 v24, v1, v25
	v_min_u32_e32 v1, v1, v25
	v_max_u32_e32 v25, v3, v27
	v_min_u32_e32 v3, v3, v27
	v_max_u32_e32 v27, v4, v28
	v_min_u32_e32 v4, v4, v28
	v_max_u32_e32 v28, v5, v29
	v_min_u32_e32 v5, v5, v29
	v_max_u32_e32 v29, v22, v30
	v_min_u32_e32 v22, v22, v30
	v_max_u32_e32 v30, v23, v31
	v_min_u32_e32 v23, v23, v31
	v_max_u32_e32 v31, v34, v27
	v_min_u32_e32 v27, v34, v27
	v_max_u32_e32 v34, v26, v28
	v_min_u32_e32 v26, v26, v28
	v_max_u32_e32 v28, v24, v29
	v_min_u32_e32 v24, v24, v29
	v_max_u32_e32 v29, v25, v30
	v_min_u32_e32 v25, v25, v30
	v_max_u32_e32 v30, v2, v4
	v_min_u32_e32 v2, v2, v4
	v_max_u32_e32 v4, v0, v5
	v_min_u32_e32 v0, v0, v5
	v_max_u32_e32 v5, v1, v22
	v_min_u32_e32 v1, v1, v22
	v_max_u32_e32 v22, v3, v23
	v_min_u32_e32 v3, v3, v23
	v_max_u32_e32 v23, v31, v28
	v_min_u32_e32 v28, v31, v28
	v_max_u32_e32 v31, v34, v29
	v_max_u32_e32 v51, v30, v5
	v_max_u32_e32 v52, v4, v22
	v_min_u32_e32 v4, v4, v22
	v_max_u32_e32 v53, v2, v1
	v_min_u32_e32 v1, v2, v1
	v_max_u32_e32 v2, v0, v3
	v_min_u32_e32 v0, v0, v3
	v_max_u32_e32 v22, v23, v31
	v_cmp_lt_i32_e32 vcc, -1, v6
	v_min_u32_e32 v5, v30, v5
	v_min_u32_e32 v23, v23, v31
	v_max_u32_e32 v30, v51, v52
	v_min_u32_e32 v31, v51, v52
	v_max_u32_e32 v51, v53, v2
	v_min_u32_e32 v52, v53, v2
	v_max_u32_e32 v53, v1, v0
	v_min_u32_e32 v61, v1, v0
	v_cndmask_b32_e64 v0, v58, -1, vcc
	v_cmp_lt_i32_e32 vcc, -1, v22
	v_bitop3_b32 v77, v0, v6, s24 bitop3:0x78
	v_min_u32_e32 v29, v34, v29
	v_cndmask_b32_e64 v0, v58, -1, vcc
	v_cmp_lt_i32_e32 vcc, -1, v10
	v_bitop3_b32 v0, v0, v22, s24 bitop3:0x78
	v_max_u32_e32 v34, v27, v24
	v_cndmask_b32_e64 v1, v58, -1, vcc
	v_cmp_lt_i32_e32 vcc, -1, v23
	v_min_u32_e32 v43, v27, v24
	v_max_u32_e32 v24, v28, v29
	v_bitop3_b32 v73, v1, v10, s24 bitop3:0x78
	v_cndmask_b32_e64 v1, v58, -1, vcc
	v_cmp_lt_i32_e32 vcc, -1, v9
	v_add_f32_e32 v86, v77, v0
	v_bitop3_b32 v62, v1, v23, s24 bitop3:0x78
	v_cndmask_b32_e64 v1, v58, -1, vcc
	v_cmp_lt_i32_e32 vcc, -1, v24
	v_ashrrev_i32_e32 v87, 31, v86
	v_bitop3_b32 v71, v1, v9, s24 bitop3:0x78
	v_cndmask_b32_e64 v1, v58, -1, vcc
	v_or_b32_e32 v87, 0x80000000, v87
	v_bitop3_b32 v67, v1, v24, s24 bitop3:0x78
	v_bitop3_b32 v86, v87, s25, v86 bitop3:0xde
	v_add_f32_e32 v87, v77, v62
	v_ashrrev_i32_e32 v88, 31, v87
	v_add_f32_e32 v90, v77, v67
	v_max_u32_e32 v27, v26, v25
	v_min_u32_e32 v50, v26, v25
	v_min_u32_e32 v25, v28, v29
	v_cmp_lt_i32_e32 vcc, -1, v13
	v_or_b32_e32 v88, 0x80000000, v88
	v_ashrrev_i32_e32 v91, 31, v90
	v_cndmask_b32_e64 v1, v58, -1, vcc
	v_cmp_lt_i32_e32 vcc, -1, v25
	v_bitop3_b32 v87, v88, s26, v87 bitop3:0x48
	v_or_b32_e32 v91, 0x80000000, v91
	v_bitop3_b32 v69, v1, v13, s24 bitop3:0x78
	v_cndmask_b32_e64 v1, v58, -1, vcc
	v_or_b32_e32 v87, 0xfe, v87
	v_bitop3_b32 v90, v91, s26, v90 bitop3:0x48
	v_bitop3_b32 v70, v1, v25, s24 bitop3:0x78
	v_max_u32_e32 v88, v86, v87
	v_or_b32_e32 v90, 0xfd, v90
	v_min_u32_e32 v89, v86, v87
	v_max_u32_e32 v91, v88, v90
	v_min_u32_e32 v88, v88, v90
	v_med3_u32 v86, v86, v87, v90
	v_add_f32_e32 v90, v77, v70
	v_ashrrev_i32_e32 v92, 31, v90
	v_max_u32_e32 v26, v34, v27
	v_cmp_lt_i32_e32 vcc, -1, v8
	v_or_b32_e32 v92, 0x80000000, v92
	v_bitop3_b32 v90, v92, s26, v90 bitop3:0x48
	v_cndmask_b32_e64 v1, v58, -1, vcc
	v_cmp_lt_i32_e32 vcc, -1, v26
	v_bitop3_b32 v68, v1, v8, s24 bitop3:0x78
	v_or_b32_e32 v90, 0xfc, v90
	v_cndmask_b32_e64 v1, v58, -1, vcc
	v_bitop3_b32 v72, v1, v26, s24 bitop3:0x78
	v_max_u32_e32 v92, v91, v90
	v_min_u32_e32 v90, v91, v90
	v_min_u32_e32 v87, v89, v88
	v_max_u32_e32 v91, v86, v90
	v_min_u32_e32 v86, v86, v90
	v_med3_u32 v88, v89, v88, v90
	v_add_f32_e32 v90, v77, v72
	v_ashrrev_i32_e32 v93, 31, v90
	v_or_b32_e32 v93, 0x80000000, v93
	v_min_u32_e32 v27, v34, v27
	v_cmp_lt_i32_e32 vcc, -1, v14
	v_bitop3_b32 v90, v93, s26, v90 bitop3:0x48
	v_or_b32_e32 v90, 0xfb, v90
	v_cndmask_b32_e64 v1, v58, -1, vcc
	v_cmp_lt_i32_e32 vcc, -1, v27
	v_bitop3_b32 v66, v1, v14, s24 bitop3:0x78
	v_max_u32_e32 v93, v92, v90
	v_cndmask_b32_e64 v1, v58, -1, vcc
	v_min_u32_e32 v90, v92, v90
	v_bitop3_b32 v76, v1, v27, s24 bitop3:0x78
	v_max_u32_e32 v92, v91, v90
	v_min_u32_e32 v90, v91, v90
	v_min_u32_e32 v89, v87, v86
	v_max_u32_e32 v91, v88, v90
	v_min_u32_e32 v88, v88, v90
	v_med3_u32 v86, v87, v86, v90
	v_add_f32_e32 v90, v77, v76
	v_ashrrev_i32_e32 v94, 31, v90
	v_or_b32_e32 v94, 0x80000000, v94
	v_bitop3_b32 v90, v94, s26, v90 bitop3:0x48
	v_max_u32_e32 v28, v43, v50
	v_cmp_lt_i32_e32 vcc, -1, v12
	v_or_b32_e32 v90, 0xfa, v90
	v_max_u32_e32 v94, v93, v90
	v_cndmask_b32_e64 v1, v58, -1, vcc
	v_cmp_lt_i32_e32 vcc, -1, v28
	v_min_u32_e32 v90, v93, v90
	v_bitop3_b32 v65, v1, v12, s24 bitop3:0x78
	v_cndmask_b32_e64 v1, v58, -1, vcc
	v_max_u32_e32 v93, v92, v90
	v_min_u32_e32 v90, v92, v90
	v_bitop3_b32 v75, v1, v28, s24 bitop3:0x78
	v_max_u32_e32 v92, v91, v90
	v_min_u32_e32 v90, v91, v90
	v_min_u32_e32 v87, v89, v88
	v_max_u32_e32 v91, v86, v90
	v_min_u32_e32 v86, v86, v90
	v_med3_u32 v88, v89, v88, v90
	v_add_f32_e32 v90, v77, v75
	v_ashrrev_i32_e32 v95, 31, v90
	v_or_b32_e32 v95, 0x80000000, v95
	v_bitop3_b32 v90, v95, s26, v90 bitop3:0x48
; __device__ __forceinline__ void ins16(u32 (&top)[16], u32 v) {
; #pragma unroll
;   for (int j = 0; j < 16; ++j) {
;     u32 hi = max(top[j], v);
;     v = min(top[j], v);
;     top[j] = hi;
;   }
; }
; __device__ void topk_phase(const Params& p) {
;     ...
; #pragma unroll
;       for (int i = 0; i < 16; ++i)
; #pragma unroll
;         for (int j = 0; j < 16; ++j)
;           if ((i + 1) * (j + 1) <= 16) {
;             const u32 v = (ord_enc(sa[i] + sb[j]) | 255u) ^ (u32)(i * 16 + j);
;             ins16(top, v);
;           }
	v_or_b32_e32 v90, 0xf9, v90
	v_min_u32_e32 v29, v43, v50
	v_cmp_lt_i32_e32 vcc, -1, v16
	v_max_u32_e32 v95, v94, v90
	v_min_u32_e32 v90, v94, v90
	v_cndmask_b32_e64 v1, v58, -1, vcc
	v_cmp_lt_i32_e32 vcc, -1, v29
	v_max_u32_e32 v94, v93, v90
	v_min_u32_e32 v90, v93, v90
	v_bitop3_b32 v64, v1, v16, s24 bitop3:0x78
	v_cndmask_b32_e64 v1, v58, -1, vcc
	v_max_u32_e32 v93, v92, v90
	v_min_u32_e32 v90, v92, v90
	v_bitop3_b32 v74, v1, v29, s24 bitop3:0x78
	v_max_u32_e32 v92, v91, v90
	v_min_u32_e32 v90, v91, v90
	v_min_u32_e32 v89, v87, v86
	v_max_u32_e32 v91, v88, v90
	v_min_u32_e32 v88, v88, v90
	v_med3_u32 v86, v87, v86, v90
	v_add_f32_e32 v90, v77, v74
	v_ashrrev_i32_e32 v96, 31, v90
	v_or_b32_e32 v96, 0x80000000, v96
	v_bitop3_b32 v90, v96, s26, v90 bitop3:0x48
	v_or_b32_e32 v90, 0xf8, v90
	v_cmp_lt_i32_e32 vcc, -1, v7
	v_max_u32_e32 v96, v95, v90
	v_min_u32_e32 v90, v95, v90
	v_cndmask_b32_e64 v1, v58, -1, vcc
	v_cmp_lt_i32_e32 vcc, -1, v30
	v_max_u32_e32 v95, v94, v90
	v_min_u32_e32 v90, v94, v90
	v_bitop3_b32 v63, v1, v7, s24 bitop3:0x78
	v_cndmask_b32_e64 v1, v58, -1, vcc
	v_max_u32_e32 v94, v93, v90
	v_min_u32_e32 v90, v93, v90
	v_bitop3_b32 v78, v1, v30, s24 bitop3:0x78
	v_max_u32_e32 v93, v92, v90
	v_min_u32_e32 v90, v92, v90
	v_max_u32_e32 v92, v91, v90
	v_min_u32_e32 v90, v91, v90
	v_add_f32_e32 v78, v77, v78
	v_min_u32_e32 v87, v89, v88
	v_max_u32_e32 v91, v86, v90
	v_min_u32_e32 v86, v86, v90
	v_med3_u32 v88, v89, v88, v90
	v_ashrrev_i32_e32 v90, 31, v78
	v_or_b32_e32 v90, 0x80000000, v90
	v_bitop3_b32 v78, v90, s26, v78 bitop3:0x48
	v_or_b32_e32 v78, 0xf7, v78
	v_max_u32_e32 v90, v96, v78
	v_min_u32_e32 v78, v96, v78
	v_cmp_lt_i32_e32 vcc, -1, v18
	v_max_u32_e32 v96, v95, v78
	v_min_u32_e32 v78, v95, v78
	v_cndmask_b32_e64 v1, v58, -1, vcc
	v_cmp_lt_i32_e32 vcc, -1, v31
	v_max_u32_e32 v95, v94, v78
	v_min_u32_e32 v78, v94, v78
	v_bitop3_b32 v60, v1, v18, s24 bitop3:0x78
	v_cndmask_b32_e64 v1, v58, -1, vcc
	v_max_u32_e32 v94, v93, v78
	v_min_u32_e32 v78, v93, v78
	v_bitop3_b32 v79, v1, v31, s24 bitop3:0x78
	v_max_u32_e32 v93, v92, v78
	v_min_u32_e32 v78, v92, v78
	v_max_u32_e32 v92, v91, v78
	v_min_u32_e32 v78, v91, v78
	v_add_f32_e32 v79, v77, v79
	v_min_u32_e32 v89, v87, v86
	v_max_u32_e32 v91, v88, v78
	v_min_u32_e32 v88, v88, v78
	v_med3_u32 v78, v87, v86, v78
	v_ashrrev_i32_e32 v87, 31, v79
	v_or_b32_e32 v87, 0x80000000, v87
	v_bitop3_b32 v79, v87, s26, v79 bitop3:0x48
	v_or_b32_e32 v79, 0xf6, v79
	v_max_u32_e32 v87, v90, v79
	v_min_u32_e32 v79, v90, v79
	v_max_u32_e32 v90, v96, v79
	v_min_u32_e32 v79, v96, v79
	v_max_u32_e32 v43, v5, v4
	v_cmp_lt_i32_e32 vcc, -1, v15
	v_max_u32_e32 v96, v95, v79
	v_min_u32_e32 v79, v95, v79
	v_cndmask_b32_e64 v1, v58, -1, vcc
	v_cmp_lt_i32_e32 vcc, -1, v43
	v_max_u32_e32 v95, v94, v79
	v_min_u32_e32 v79, v94, v79
	v_bitop3_b32 v34, v1, v15, s24 bitop3:0x78
	v_cndmask_b32_e64 v1, v58, -1, vcc
	v_max_u32_e32 v94, v93, v79
	v_min_u32_e32 v79, v93, v79
	v_bitop3_b32 v80, v1, v43, s24 bitop3:0x78
	v_max_u32_e32 v93, v92, v79
	v_min_u32_e32 v79, v92, v79
	v_max_u32_e32 v92, v91, v79
	v_min_u32_e32 v79, v91, v79
	v_add_f32_e32 v80, v77, v80
	v_min_u32_e32 v86, v89, v88
	v_max_u32_e32 v91, v78, v79
	v_min_u32_e32 v78, v78, v79
	v_med3_u32 v79, v89, v88, v79
	v_ashrrev_i32_e32 v89, 31, v80
	v_or_b32_e32 v89, 0x80000000, v89
	v_bitop3_b32 v80, v89, s26, v80 bitop3:0x48
	v_or_b32_e32 v80, 0xf5, v80
	v_max_u32_e32 v89, v87, v80
	v_min_u32_e32 v80, v87, v80
	v_max_u32_e32 v87, v90, v80
	v_med3_u32 v90, v90, v96, v80
	v_min_u32_e32 v50, v5, v4
	v_cmp_lt_i32_e32 vcc, -1, v19
	v_med3_u32 v96, v96, v95, v80
	v_cndmask_b32_e64 v1, v58, -1, vcc
	v_cmp_lt_i32_e32 vcc, -1, v50
	v_med3_u32 v95, v95, v94, v80
	v_bitop3_b32 v5, v1, v19, s24 bitop3:0x78
	v_cndmask_b32_e64 v1, v58, -1, vcc
	v_med3_u32 v94, v94, v93, v80
	v_bitop3_b32 v81, v1, v50, s24 bitop3:0x78
	v_med3_u32 v93, v93, v92, v80
	v_med3_u32 v92, v92, v91, v80
	v_min_u32_e32 v80, v91, v80
	v_add_f32_e32 v81, v77, v81
	v_min_u32_e32 v88, v86, v78
	v_med3_u32 v78, v86, v78, v80
	v_ashrrev_i32_e32 v86, 31, v81
	v_or_b32_e32 v86, 0x80000000, v86
	v_bitop3_b32 v81, v86, s26, v81 bitop3:0x48
	v_or_b32_e32 v81, 0xf4, v81
	v_max_u32_e32 v86, v89, v81
	v_min_u32_e32 v81, v89, v81
	v_max_u32_e32 v89, v87, v81
	v_med3_u32 v87, v87, v90, v81
	v_med3_u32 v90, v90, v96, v81
	v_cmp_lt_i32_e32 vcc, -1, v11
	v_med3_u32 v96, v96, v95, v81
	v_cndmask_b32_e64 v1, v58, -1, vcc
	v_cmp_lt_i32_e32 vcc, -1, v51
	v_med3_u32 v95, v95, v94, v81
	v_bitop3_b32 v4, v1, v11, s24 bitop3:0x78
	v_cndmask_b32_e64 v1, v58, -1, vcc
	v_med3_u32 v94, v94, v93, v81
	v_bitop3_b32 v82, v1, v51, s24 bitop3:0x78
	v_max_u32_e32 v91, v79, v80
	v_med3_u32 v93, v93, v92, v81
	v_min_u32_e32 v79, v79, v80
	v_med3_u32 v92, v92, v91, v81
	v_min_u32_e32 v81, v91, v81
	v_add_f32_e32 v82, v77, v82
	v_min_u32_e32 v80, v88, v79
	v_med3_u32 v79, v88, v79, v81
	v_ashrrev_i32_e32 v88, 31, v82
	v_or_b32_e32 v88, 0x80000000, v88
	v_bitop3_b32 v82, v88, s26, v82 bitop3:0x48
	v_or_b32_e32 v82, 0xf3, v82
	v_max_u32_e32 v88, v86, v82
	v_min_u32_e32 v82, v86, v82
	v_max_u32_e32 v86, v89, v82
	v_med3_u32 v89, v89, v87, v82
	v_med3_u32 v87, v87, v90, v82
	v_med3_u32 v90, v90, v96, v82
	v_med3_u32 v96, v96, v95, v82
	v_cmp_lt_i32_e32 vcc, -1, v20
	v_med3_u32 v95, v95, v94, v82
	v_cndmask_b32_e64 v1, v58, -1, vcc
	v_cmp_lt_i32_e32 vcc, -1, v52
	v_med3_u32 v94, v94, v93, v82
	v_bitop3_b32 v3, v1, v20, s24 bitop3:0x78
	v_cndmask_b32_e64 v1, v58, -1, vcc
	v_max_u32_e32 v91, v78, v81
	v_med3_u32 v93, v93, v92, v82
	v_bitop3_b32 v83, v1, v52, s24 bitop3:0x78
	v_min_u32_e32 v78, v78, v81
	v_med3_u32 v92, v92, v91, v82
; __device__ __forceinline__ void ins16(u32 (&top)[16], u32 v) {
; #pragma unroll
;   for (int j = 0; j < 16; ++j) {
;     u32 hi = max(top[j], v);
;     v = min(top[j], v);
;     top[j] = hi;
;   }
; }
; __device__ void topk_phase(const Params& p) {
;     ...
; #pragma unroll
;       for (int i = 0; i < 16; ++i)
; #pragma unroll
;         for (int j = 0; j < 16; ++j)
;           if ((i + 1) * (j + 1) <= 16) {
;             const u32 v = (ord_enc(sa[i] + sb[j]) | 255u) ^ (u32)(i * 16 + j);
;             ins16(top, v);
;           }
	v_min_u32_e32 v82, v91, v82
	v_min_u32_e32 v81, v80, v78
	v_max_u32_e32 v91, v79, v82
	v_min_u32_e32 v79, v79, v82
	v_med3_u32 v78, v80, v78, v82
	v_add_f32_e32 v82, v77, v83
	v_ashrrev_i32_e32 v83, 31, v82
	v_or_b32_e32 v83, 0x80000000, v83
	v_bitop3_b32 v82, v83, s26, v82 bitop3:0x48
	v_or_b32_e32 v82, 0xf2, v82
	v_max_u32_e32 v83, v88, v82
	v_min_u32_e32 v82, v88, v82
	v_max_u32_e32 v88, v86, v82
	v_med3_u32 v86, v86, v89, v82
	v_med3_u32 v89, v89, v87, v82
	v_med3_u32 v87, v87, v90, v82
	v_med3_u32 v90, v90, v96, v82
	v_med3_u32 v96, v96, v95, v82
	v_cmp_lt_i32_e32 vcc, -1, v17
	v_med3_u32 v95, v95, v94, v82
	v_cndmask_b32_e64 v1, v58, -1, vcc
	v_cmp_lt_i32_e32 vcc, -1, v53
	v_med3_u32 v94, v94, v93, v82
	v_bitop3_b32 v2, v1, v17, s24 bitop3:0x78
	v_cndmask_b32_e64 v1, v58, -1, vcc
	v_med3_u32 v93, v93, v92, v82
	v_bitop3_b32 v84, v1, v53, s24 bitop3:0x78
	v_med3_u32 v92, v92, v91, v82
	v_min_u32_e32 v82, v91, v82
	v_min_u32_e32 v80, v81, v79
	v_max_u32_e32 v91, v78, v82
	v_min_u32_e32 v78, v78, v82
	v_med3_u32 v79, v81, v79, v82
	v_add_f32_e32 v82, v77, v84
	v_ashrrev_i32_e32 v84, 31, v82
	v_or_b32_e32 v84, 0x80000000, v84
	v_bitop3_b32 v82, v84, s26, v82 bitop3:0x48
	v_or_b32_e32 v82, 0xf1, v82
	v_max_u32_e32 v84, v83, v82
	v_min_u32_e32 v82, v83, v82
	v_max_u32_e32 v83, v88, v82
	v_med3_u32 v88, v88, v86, v82
	v_med3_u32 v86, v86, v89, v82
	v_med3_u32 v89, v89, v87, v82
	v_med3_u32 v87, v87, v90, v82
	v_med3_u32 v90, v90, v96, v82
	v_cmp_lt_i32_e32 vcc, -1, v21
	v_med3_u32 v96, v96, v95, v82
	v_cndmask_b32_e64 v1, v58, -1, vcc
	v_cmp_lt_i32_e32 vcc, -1, v61
	v_med3_u32 v95, v95, v94, v82
	v_cndmask_b32_e64 v85, v58, -1, vcc
	v_med3_u32 v94, v94, v93, v82
	v_bitop3_b32 v85, v85, v61, s24 bitop3:0x78
	v_med3_u32 v93, v93, v92, v82
	v_med3_u32 v92, v92, v91, v82
	v_min_u32_e32 v82, v91, v82
	v_add_f32_e32 v77, v77, v85
	v_min_u32_e32 v81, v80, v78
	v_max_u32_e32 v91, v79, v82
	v_min_u32_e32 v79, v79, v82
	v_med3_u32 v78, v80, v78, v82
	v_ashrrev_i32_e32 v82, 31, v77
	v_or_b32_e32 v82, 0x80000000, v82
	v_bitop3_b32 v77, v82, s26, v77 bitop3:0x48
	v_or_b32_e32 v77, 0xf0, v77
	v_max_u32_e32 v82, v84, v77
	v_min_u32_e32 v77, v84, v77
	v_max_u32_e32 v84, v83, v77
	v_med3_u32 v83, v83, v88, v77
	v_med3_u32 v85, v88, v86, v77
	v_med3_u32 v86, v86, v89, v77
	v_med3_u32 v88, v89, v87, v77
	v_med3_u32 v87, v87, v90, v77
	v_med3_u32 v89, v90, v96, v77
	v_med3_u32 v90, v96, v95, v77
	v_med3_u32 v95, v95, v94, v77
	v_med3_u32 v94, v94, v93, v77
	v_med3_u32 v93, v93, v92, v77
	v_med3_u32 v92, v92, v91, v77
	v_min_u32_e32 v77, v91, v77
	v_min_u32_e32 v80, v81, v79
	v_max_u32_e32 v91, v78, v77
	v_min_u32_e32 v78, v78, v77
	v_med3_u32 v77, v81, v79, v77
	v_add_f32_e32 v79, v73, v0
	v_min_u32_e32 v78, v80, v78
	v_ashrrev_i32_e32 v80, 31, v79
	v_or_b32_e32 v80, 0x80000000, v80
	v_bitop3_b32 v79, v80, s26, v79 bitop3:0x48
	v_or_b32_e32 v79, 0xef, v79
	v_max_u32_e32 v80, v82, v79
	v_min_u32_e32 v79, v82, v79
	v_max_u32_e32 v81, v84, v79
	v_med3_u32 v82, v84, v83, v79
	v_med3_u32 v83, v83, v85, v79
	v_med3_u32 v84, v85, v86, v79
	v_med3_u32 v85, v86, v88, v79
	v_med3_u32 v86, v88, v87, v79
	v_med3_u32 v87, v87, v89, v79
	v_med3_u32 v88, v89, v90, v79
	v_med3_u32 v89, v90, v95, v79
	v_med3_u32 v90, v95, v94, v79
	v_med3_u32 v94, v94, v93, v79
	v_med3_u32 v93, v93, v92, v79
	v_med3_u32 v92, v92, v91, v79
	v_min_u32_e32 v79, v91, v79
	v_max_u32_e32 v91, v77, v79
	v_min_u32_e32 v77, v77, v79
	v_add_f32_e32 v79, v73, v62
	v_ashrrev_i32_e32 v95, 31, v79
	v_or_b32_e32 v95, 0x80000000, v95
	v_bitop3_b32 v79, v95, s26, v79 bitop3:0x48
	v_or_b32_e32 v79, 0xee, v79
	v_max_u32_e32 v95, v80, v79
	v_min_u32_e32 v79, v80, v79
	v_max_u32_e32 v80, v81, v79
	v_med3_u32 v81, v81, v82, v79
	v_med3_u32 v82, v82, v83, v79
	v_med3_u32 v83, v83, v84, v79
	v_med3_u32 v84, v84, v85, v79
	v_med3_u32 v85, v85, v86, v79
	v_med3_u32 v86, v86, v87, v79
	v_med3_u32 v87, v87, v88, v79
	v_med3_u32 v88, v88, v89, v79
	v_med3_u32 v89, v89, v90, v79
	v_med3_u32 v90, v90, v94, v79
	v_med3_u32 v94, v94, v93, v79
	v_med3_u32 v93, v93, v92, v79
	v_med3_u32 v92, v92, v91, v79
	v_min_u32_e32 v79, v91, v79
	v_max3_u32 v77, v78, v77, v79
	v_add_f32_e32 v78, v73, v67
	v_ashrrev_i32_e32 v79, 31, v78
	v_or_b32_e32 v79, 0x80000000, v79
	v_bitop3_b32 v78, v79, s26, v78 bitop3:0x48
	v_or_b32_e32 v78, 0xed, v78
	v_max_u32_e32 v79, v95, v78
	v_min_u32_e32 v78, v95, v78
	v_max_u32_e32 v91, v80, v78
	v_med3_u32 v80, v80, v81, v78
	v_med3_u32 v81, v81, v82, v78
	v_med3_u32 v82, v82, v83, v78
	v_med3_u32 v83, v83, v84, v78
	v_med3_u32 v84, v84, v85, v78
	v_med3_u32 v85, v85, v86, v78
	v_med3_u32 v86, v86, v87, v78
	v_med3_u32 v87, v87, v88, v78
	v_med3_u32 v88, v88, v89, v78
	v_med3_u32 v89, v89, v90, v78
	v_med3_u32 v90, v90, v94, v78
	v_med3_u32 v94, v94, v93, v78
	v_med3_u32 v93, v93, v92, v78
	v_min_u32_e32 v78, v92, v78
	v_add_f32_e32 v92, v73, v70
	v_ashrrev_i32_e32 v95, 31, v92
	v_or_b32_e32 v95, 0x80000000, v95
	v_bitop3_b32 v92, v95, s26, v92 bitop3:0x48
	v_or_b32_e32 v92, 0xec, v92
	v_max_u32_e32 v95, v79, v92
	v_min_u32_e32 v79, v79, v92
	v_max_u32_e32 v92, v91, v79
	v_med3_u32 v91, v91, v80, v79
	v_med3_u32 v80, v80, v81, v79
	v_med3_u32 v81, v81, v82, v79
	v_med3_u32 v82, v82, v83, v79
	v_med3_u32 v83, v83, v84, v79
	v_med3_u32 v84, v84, v85, v79
	v_med3_u32 v85, v85, v86, v79
	v_med3_u32 v86, v86, v87, v79
	v_med3_u32 v87, v87, v88, v79
	v_med3_u32 v88, v88, v89, v79
	v_med3_u32 v89, v89, v90, v79
	v_med3_u32 v90, v90, v94, v79
	v_med3_u32 v94, v94, v93, v79
	v_min_u32_e32 v79, v93, v79
	v_max3_u32 v77, v77, v78, v79
	v_add_f32_e32 v78, v73, v72
	v_ashrrev_i32_e32 v79, 31, v78
; __device__ __forceinline__ void ins16(u32 (&top)[16], u32 v) {
; #pragma unroll
;   for (int j = 0; j < 16; ++j) {
;     u32 hi = max(top[j], v);
;     v = min(top[j], v);
;     top[j] = hi;
;   }
; }
; __device__ void topk_phase(const Params& p) {
;     ...
;       for (int j = 0; j < 16; ++j) { sa[j] = ord_dec(lists[0][j] & ~127u); sb[j] = ord_dec(lists[1][j] & ~127u); }
;       u32 top[16];
; #pragma unroll
;       for (int j = 0; j < 16; ++j) top[j] = 0u;
; #pragma unroll
;       for (int i = 0; i < 16; ++i)
; #pragma unroll
;         for (int j = 0; j < 16; ++j)
;           if ((i + 1) * (j + 1) <= 16) {
;             const u32 v = (ord_enc(sa[i] + sb[j]) | 255u) ^ (u32)(i * 16 + j);
;             ins16(top, v);
;           }
	v_or_b32_e32 v79, 0x80000000, v79
	v_bitop3_b32 v78, v79, s26, v78 bitop3:0x48
	v_or_b32_e32 v78, 0xeb, v78
	v_max_u32_e32 v79, v95, v78
	v_min_u32_e32 v78, v95, v78
	v_max_u32_e32 v93, v92, v78
	v_med3_u32 v92, v92, v91, v78
	v_med3_u32 v91, v91, v80, v78
	v_med3_u32 v80, v80, v81, v78
	v_med3_u32 v81, v81, v82, v78
	v_med3_u32 v82, v82, v83, v78
	v_med3_u32 v83, v83, v84, v78
	v_med3_u32 v84, v84, v85, v78
	v_med3_u32 v85, v85, v86, v78
	v_med3_u32 v86, v86, v87, v78
	v_med3_u32 v87, v87, v88, v78
	v_med3_u32 v88, v88, v89, v78
	v_med3_u32 v89, v89, v90, v78
	v_add_f32_e32 v76, v73, v76
	v_med3_u32 v90, v90, v94, v78
	v_min_u32_e32 v78, v94, v78
	v_ashrrev_i32_e32 v94, 31, v76
	v_or_b32_e32 v94, 0x80000000, v94
	v_bitop3_b32 v76, v94, s26, v76 bitop3:0x48
	v_or_b32_e32 v76, 0xea, v76
	v_max_u32_e32 v94, v79, v76
	v_min_u32_e32 v76, v79, v76
	v_max_u32_e32 v79, v93, v76
	v_med3_u32 v93, v93, v92, v76
	v_med3_u32 v92, v92, v91, v76
	v_med3_u32 v91, v91, v80, v76
	v_med3_u32 v80, v80, v81, v76
	v_med3_u32 v81, v81, v82, v76
	v_med3_u32 v82, v82, v83, v76
	v_med3_u32 v83, v83, v84, v76
	v_med3_u32 v84, v84, v85, v76
	v_med3_u32 v85, v85, v86, v76
	v_med3_u32 v86, v86, v87, v76
	v_med3_u32 v87, v87, v88, v76
	v_med3_u32 v88, v88, v89, v76
	v_med3_u32 v89, v89, v90, v76
	v_min_u32_e32 v76, v90, v76
	v_add_f32_e32 v75, v73, v75
	v_max3_u32 v76, v77, v78, v76
	v_ashrrev_i32_e32 v77, 31, v75
	v_or_b32_e32 v77, 0x80000000, v77
	v_bitop3_b32 v75, v77, s26, v75 bitop3:0x48
	v_or_b32_e32 v75, 0xe9, v75
	v_max_u32_e32 v77, v94, v75
	v_min_u32_e32 v75, v94, v75
	v_max_u32_e32 v78, v79, v75
	v_med3_u32 v79, v79, v93, v75
	v_med3_u32 v90, v93, v92, v75
	v_med3_u32 v92, v92, v91, v75
	v_med3_u32 v91, v91, v80, v75
	v_add_f32_e32 v73, v73, v74
	v_med3_u32 v80, v80, v81, v75
	v_ashrrev_i32_e32 v74, 31, v73
	v_med3_u32 v81, v81, v82, v75
	v_or_b32_e32 v74, 0x80000000, v74
	v_med3_u32 v82, v82, v83, v75
	v_bitop3_b32 v73, v74, s26, v73 bitop3:0x48
	v_med3_u32 v83, v83, v84, v75
	v_or_b32_e32 v73, 0xe8, v73
	v_med3_u32 v84, v84, v85, v75
	v_min_u32_e32 v75, v85, v75
	v_max_u32_e32 v74, v77, v73
	v_min_u32_e32 v73, v77, v73
	v_max_u32_e32 v85, v86, v75
	v_min_u32_e32 v75, v86, v75
	v_max_u32_e32 v77, v78, v73
	v_min_u32_e32 v73, v78, v73
	v_max_u32_e32 v86, v87, v75
	v_min_u32_e32 v75, v87, v75
	v_max_u32_e32 v78, v79, v73
	v_min_u32_e32 v73, v79, v73
	v_max_u32_e32 v87, v88, v75
	v_min_u32_e32 v75, v88, v75
	v_max_u32_e32 v79, v90, v73
	v_min_u32_e32 v73, v90, v73
	v_max_u32_e32 v88, v89, v75
	v_min_u32_e32 v75, v89, v75
	v_max_u32_e32 v89, v92, v73
	v_min_u32_e32 v73, v92, v73
	v_max_u32_e32 v90, v91, v73
	v_med3_u32 v91, v91, v80, v73
	v_med3_u32 v80, v80, v81, v73
	v_med3_u32 v81, v81, v82, v73
	v_med3_u32 v82, v82, v83, v73
	v_med3_u32 v83, v83, v84, v73
	v_med3_u32 v84, v84, v85, v73
	v_med3_u32 v85, v85, v86, v73
	v_med3_u32 v86, v86, v87, v73
	v_med3_u32 v87, v87, v88, v73
	v_min_u32_e32 v73, v88, v73
	v_max3_u32 v73, v76, v75, v73
	v_add_f32_e32 v75, v71, v0
	v_ashrrev_i32_e32 v76, 31, v75
	v_or_b32_e32 v76, 0x80000000, v76
	v_bitop3_b32 v75, v76, s26, v75 bitop3:0x48
	v_or_b32_e32 v75, 0xdf, v75
	v_max_u32_e32 v76, v74, v75
	v_min_u32_e32 v74, v74, v75
	v_max_u32_e32 v75, v77, v74
	v_med3_u32 v77, v77, v78, v74
	v_med3_u32 v78, v78, v79, v74
	v_med3_u32 v79, v79, v89, v74
	v_med3_u32 v88, v89, v90, v74
	v_med3_u32 v89, v90, v91, v74
	v_med3_u32 v90, v91, v80, v74
	v_med3_u32 v80, v80, v81, v74
	v_med3_u32 v81, v81, v82, v74
	v_med3_u32 v82, v82, v83, v74
	v_med3_u32 v83, v83, v84, v74
	v_med3_u32 v84, v84, v85, v74
	v_med3_u32 v85, v85, v86, v74
	v_med3_u32 v86, v86, v87, v74
	v_min_u32_e32 v74, v87, v74
	v_add_f32_e32 v87, v71, v62
	v_ashrrev_i32_e32 v91, 31, v87
	v_or_b32_e32 v91, 0x80000000, v91
	v_bitop3_b32 v87, v91, s26, v87 bitop3:0x48
	v_or_b32_e32 v87, 0xde, v87
	v_max_u32_e32 v91, v76, v87
	v_min_u32_e32 v76, v76, v87
	v_max_u32_e32 v87, v75, v76
	v_min_u32_e32 v75, v75, v76
	v_max_u32_e32 v76, v77, v75
	v_med3_u32 v77, v77, v78, v75
	v_med3_u32 v78, v78, v79, v75
	v_med3_u32 v79, v79, v88, v75
	v_med3_u32 v88, v88, v89, v75
	v_med3_u32 v89, v89, v90, v75
	v_med3_u32 v90, v90, v80, v75
	v_med3_u32 v80, v80, v81, v75
	v_med3_u32 v81, v81, v82, v75
	v_med3_u32 v82, v82, v83, v75
	v_med3_u32 v83, v83, v84, v75
	v_med3_u32 v84, v84, v85, v75
	v_med3_u32 v85, v85, v86, v75
	v_min_u32_e32 v75, v86, v75
	v_max3_u32 v73, v73, v74, v75
	v_add_f32_e32 v74, v71, v67
	v_ashrrev_i32_e32 v75, 31, v74
	v_or_b32_e32 v75, 0x80000000, v75
	v_bitop3_b32 v74, v75, s26, v74 bitop3:0x48
	v_or_b32_e32 v74, 0xdd, v74
	v_max_u32_e32 v75, v91, v74
	v_min_u32_e32 v74, v91, v74
	v_max_u32_e32 v86, v87, v74
	v_med3_u32 v87, v87, v76, v74
	v_med3_u32 v76, v76, v77, v74
	v_med3_u32 v77, v77, v78, v74
	v_med3_u32 v78, v78, v79, v74
	v_med3_u32 v79, v79, v88, v74
	v_med3_u32 v88, v88, v89, v74
	v_med3_u32 v89, v89, v90, v74
	v_med3_u32 v90, v90, v80, v74
	v_med3_u32 v80, v80, v81, v74
	v_med3_u32 v81, v81, v82, v74
	v_med3_u32 v82, v82, v83, v74
	v_med3_u32 v83, v83, v84, v74
	v_med3_u32 v84, v84, v85, v74
	v_min_u32_e32 v74, v85, v74
	v_add_f32_e32 v85, v71, v70
	v_ashrrev_i32_e32 v91, 31, v85
	v_or_b32_e32 v91, 0x80000000, v91
	v_bitop3_b32 v85, v91, s26, v85 bitop3:0x48
	v_or_b32_e32 v85, 0xdc, v85
	v_max_u32_e32 v91, v75, v85
	v_min_u32_e32 v75, v75, v85
	v_max_u32_e32 v85, v86, v75
	v_med3_u32 v86, v86, v87, v75
	v_med3_u32 v87, v87, v76, v75
	v_med3_u32 v76, v76, v77, v75
	v_med3_u32 v77, v77, v78, v75
	v_med3_u32 v78, v78, v79, v75
	v_med3_u32 v79, v79, v88, v75
	v_med3_u32 v88, v88, v89, v75
	v_med3_u32 v89, v89, v90, v75
	v_add_f32_e32 v71, v71, v72
; __device__ __forceinline__ void ins16(u32 (&top)[16], u32 v) {
; #pragma unroll
;   for (int j = 0; j < 16; ++j) {
;     u32 hi = max(top[j], v);
;     v = min(top[j], v);
;     top[j] = hi;
;   }
; }
; __device__ void topk_phase(const Params& p) {
;     ...
;       for (int j = 0; j < 16; ++j) { sa[j] = ord_dec(lists[0][j] & ~127u); sb[j] = ord_dec(lists[1][j] & ~127u); }
;       u32 top[16];
; #pragma unroll
;       for (int j = 0; j < 16; ++j) top[j] = 0u;
; #pragma unroll
;       for (int i = 0; i < 16; ++i)
; #pragma unroll
;         for (int j = 0; j < 16; ++j)
;           if ((i + 1) * (j + 1) <= 16) {
;             const u32 v = (ord_enc(sa[i] + sb[j]) | 255u) ^ (u32)(i * 16 + j);
;             ins16(top, v);
;           }
	v_med3_u32 v90, v90, v80, v75
	v_ashrrev_i32_e32 v72, 31, v71
	v_med3_u32 v80, v80, v81, v75
	v_or_b32_e32 v72, 0x80000000, v72
	v_med3_u32 v81, v81, v82, v75
	v_bitop3_b32 v71, v72, s26, v71 bitop3:0x48
	v_med3_u32 v82, v82, v83, v75
	v_or_b32_e32 v71, 0xdb, v71
	v_med3_u32 v83, v83, v84, v75
	v_min_u32_e32 v75, v84, v75
	v_max_u32_e32 v72, v91, v71
	v_min_u32_e32 v71, v91, v71
	v_max3_u32 v73, v73, v74, v75
	v_max_u32_e32 v74, v85, v71
	v_med3_u32 v75, v85, v86, v71
	v_med3_u32 v84, v86, v87, v71
	v_med3_u32 v85, v87, v76, v71
	v_med3_u32 v76, v76, v77, v71
	v_med3_u32 v77, v77, v78, v71
	v_med3_u32 v78, v78, v79, v71
	v_med3_u32 v79, v79, v88, v71
	v_med3_u32 v86, v88, v89, v71
	v_med3_u32 v87, v89, v90, v71
	v_med3_u32 v88, v90, v80, v71
	v_med3_u32 v80, v80, v81, v71
	v_med3_u32 v81, v81, v82, v71
	v_med3_u32 v82, v82, v83, v71
	v_min_u32_e32 v71, v83, v71
	v_add_f32_e32 v83, v69, v0
	v_ashrrev_i32_e32 v89, 31, v83
	v_or_b32_e32 v89, 0x80000000, v89
	v_bitop3_b32 v83, v89, s26, v83 bitop3:0x48
	v_or_b32_e32 v83, 0xcf, v83
	v_max_u32_e32 v89, v72, v83
	v_min_u32_e32 v72, v72, v83
	v_max_u32_e32 v83, v74, v72
	v_med3_u32 v74, v74, v75, v72
	v_med3_u32 v75, v75, v84, v72
	v_med3_u32 v84, v84, v85, v72
	v_med3_u32 v85, v85, v76, v72
	v_med3_u32 v76, v76, v77, v72
	v_med3_u32 v77, v77, v78, v72
	v_med3_u32 v78, v78, v79, v72
	v_med3_u32 v79, v79, v86, v72
	v_med3_u32 v86, v86, v87, v72
	v_med3_u32 v87, v87, v88, v72
	v_med3_u32 v88, v88, v80, v72
	v_med3_u32 v80, v80, v81, v72
	v_med3_u32 v81, v81, v82, v72
	v_min_u32_e32 v72, v82, v72
	v_max3_u32 v71, v73, v71, v72
	v_add_f32_e32 v72, v69, v62
	v_ashrrev_i32_e32 v73, 31, v72
	v_or_b32_e32 v73, 0x80000000, v73
	v_bitop3_b32 v72, v73, s26, v72 bitop3:0x48
	v_or_b32_e32 v72, 0xce, v72
	v_max_u32_e32 v73, v89, v72
	v_min_u32_e32 v72, v89, v72
	v_max_u32_e32 v82, v83, v72
	v_med3_u32 v83, v83, v74, v72
	v_med3_u32 v74, v74, v75, v72
	v_med3_u32 v75, v75, v84, v72
	v_med3_u32 v84, v84, v85, v72
	v_med3_u32 v85, v85, v76, v72
	v_med3_u32 v76, v76, v77, v72
	v_med3_u32 v77, v77, v78, v72
	v_med3_u32 v78, v78, v79, v72
	v_med3_u32 v79, v79, v86, v72
	v_med3_u32 v86, v86, v87, v72
	v_med3_u32 v87, v87, v88, v72
	v_med3_u32 v88, v88, v80, v72
	v_med3_u32 v80, v80, v81, v72
	v_min_u32_e32 v72, v81, v72
	v_add_f32_e32 v81, v69, v67
	v_ashrrev_i32_e32 v89, 31, v81
	v_or_b32_e32 v89, 0x80000000, v89
	v_bitop3_b32 v81, v89, s26, v81 bitop3:0x48
	v_or_b32_e32 v81, 0xcd, v81
	v_max_u32_e32 v89, v73, v81
	v_min_u32_e32 v73, v73, v81
	v_max_u32_e32 v81, v82, v73
	v_med3_u32 v82, v82, v83, v73
	v_med3_u32 v83, v83, v74, v73
	v_med3_u32 v74, v74, v75, v73
	v_med3_u32 v75, v75, v84, v73
	v_med3_u32 v84, v84, v85, v73
	v_med3_u32 v85, v85, v76, v73
	v_med3_u32 v76, v76, v77, v73
	v_med3_u32 v77, v77, v78, v73
	v_add_f32_e32 v69, v69, v70
	v_med3_u32 v78, v78, v79, v73
	v_ashrrev_i32_e32 v70, 31, v69
	v_med3_u32 v79, v79, v86, v73
	v_or_b32_e32 v70, 0x80000000, v70
	v_med3_u32 v86, v86, v87, v73
	v_bitop3_b32 v69, v70, s26, v69 bitop3:0x48
	v_med3_u32 v87, v87, v88, v73
	v_or_b32_e32 v69, 0xcc, v69
	v_med3_u32 v88, v88, v80, v73
	v_min_u32_e32 v73, v80, v73
	v_max_u32_e32 v70, v89, v69
	v_min_u32_e32 v69, v89, v69
	v_max3_u32 v71, v71, v72, v73
	v_max_u32_e32 v72, v81, v69
	v_min_u32_e32 v69, v81, v69
	v_max_u32_e32 v73, v82, v69
	v_min_u32_e32 v69, v82, v69
	v_max_u32_e32 v80, v83, v69
	v_min_u32_e32 v69, v83, v69
	v_max_u32_e32 v81, v74, v69
	v_min_u32_e32 v69, v74, v69
	v_max_u32_e32 v74, v75, v69
	v_min_u32_e32 v69, v75, v69
	v_max_u32_e32 v75, v84, v69
	v_min_u32_e32 v69, v84, v69
	v_max_u32_e32 v82, v85, v69
	v_min_u32_e32 v69, v85, v69
	v_max_u32_e32 v83, v76, v69
	v_min_u32_e32 v69, v76, v69
	v_max_u32_e32 v76, v77, v69
	v_min_u32_e32 v69, v77, v69
	v_max_u32_e32 v77, v78, v69
	v_min_u32_e32 v69, v78, v69
	v_max_u32_e32 v78, v79, v69
	v_min_u32_e32 v69, v79, v69
	v_max_u32_e32 v79, v86, v69
	v_min_u32_e32 v69, v86, v69
	v_add_f32_e32 v86, v68, v0
	v_max_u32_e32 v84, v87, v69
	v_min_u32_e32 v69, v87, v69
	v_ashrrev_i32_e32 v87, 31, v86
	v_or_b32_e32 v87, 0x80000000, v87
	v_bitop3_b32 v86, v87, s26, v86 bitop3:0x48
	v_or_b32_e32 v86, 0xbf, v86
	v_max_u32_e32 v87, v70, v86
	v_min_u32_e32 v70, v70, v86
	v_max_u32_e32 v86, v72, v70
	v_med3_u32 v72, v72, v73, v70
	v_med3_u32 v73, v73, v80, v70
	v_med3_u32 v80, v80, v81, v70
	v_med3_u32 v81, v81, v74, v70
	v_med3_u32 v74, v74, v75, v70
	v_med3_u32 v75, v75, v82, v70
	v_med3_u32 v82, v82, v83, v70
	v_med3_u32 v83, v83, v76, v70
	v_med3_u32 v76, v76, v77, v70
	v_med3_u32 v77, v77, v78, v70
	v_med3_u32 v78, v78, v79, v70
	v_max_u32_e32 v85, v88, v69
	v_med3_u32 v79, v79, v84, v70
	v_min_u32_e32 v69, v88, v69
	v_med3_u32 v84, v84, v85, v70
	v_min_u32_e32 v70, v85, v70
	v_max3_u32 v69, v71, v69, v70
	v_add_f32_e32 v70, v68, v62
	v_ashrrev_i32_e32 v71, 31, v70
	v_or_b32_e32 v71, 0x80000000, v71
	v_bitop3_b32 v70, v71, s26, v70 bitop3:0x48
	v_or_b32_e32 v70, 0xbe, v70
	v_max_u32_e32 v71, v87, v70
	v_min_u32_e32 v70, v87, v70
	v_max_u32_e32 v85, v86, v70
	v_med3_u32 v86, v86, v72, v70
	v_med3_u32 v72, v72, v73, v70
	v_med3_u32 v73, v73, v80, v70
	v_med3_u32 v80, v80, v81, v70
	v_med3_u32 v81, v81, v74, v70
	v_med3_u32 v74, v74, v75, v70
	v_add_f32_e32 v67, v68, v67
	v_med3_u32 v75, v75, v82, v70
	v_ashrrev_i32_e32 v68, 31, v67
	v_med3_u32 v82, v82, v83, v70
	v_or_b32_e32 v68, 0x80000000, v68
	v_med3_u32 v83, v83, v76, v70
	v_bitop3_b32 v67, v68, s26, v67 bitop3:0x48
	v_med3_u32 v76, v76, v77, v70
	v_or_b32_e32 v67, 0xbd, v67
	v_med3_u32 v77, v77, v78, v70
	v_min_u32_e32 v70, v78, v70
	v_max_u32_e32 v68, v71, v67
	v_min_u32_e32 v67, v71, v67
	v_max_u32_e32 v78, v79, v70
; __device__ __forceinline__ void ins16(u32 (&top)[16], u32 v) {
; #pragma unroll
;   for (int j = 0; j < 16; ++j) {
;     u32 hi = max(top[j], v);
;     v = min(top[j], v);
;     top[j] = hi;
;   }
; }
; __device__ void topk_phase(const Params& p) {
;     ...
;       for (int j = 0; j < 16; ++j) { sa[j] = ord_dec(lists[0][j] & ~127u); sb[j] = ord_dec(lists[1][j] & ~127u); }
;       u32 top[16];
; #pragma unroll
;       for (int j = 0; j < 16; ++j) top[j] = 0u;
; #pragma unroll
;       for (int i = 0; i < 16; ++i)
; #pragma unroll
;         for (int j = 0; j < 16; ++j)
;           if ((i + 1) * (j + 1) <= 16) {
;             const u32 v = (ord_enc(sa[i] + sb[j]) | 255u) ^ (u32)(i * 16 + j);
;             ins16(top, v);
;           }
	v_min_u32_e32 v70, v79, v70
	v_max_u32_e32 v71, v85, v67
	v_min_u32_e32 v67, v85, v67
	v_max_u32_e32 v79, v84, v70
	v_min_u32_e32 v70, v84, v70
	v_max_u32_e32 v84, v86, v67
	v_min_u32_e32 v67, v86, v67
	v_max_u32_e32 v85, v72, v67
	v_med3_u32 v72, v72, v73, v67
	v_med3_u32 v73, v73, v80, v67
	v_med3_u32 v80, v80, v81, v67
	v_med3_u32 v81, v81, v74, v67
	v_med3_u32 v74, v74, v75, v67
	v_med3_u32 v75, v75, v82, v67
	v_med3_u32 v82, v82, v83, v67
	v_med3_u32 v83, v83, v76, v67
	v_med3_u32 v76, v76, v77, v67
	v_med3_u32 v77, v77, v78, v67
	v_med3_u32 v78, v78, v79, v67
	v_min_u32_e32 v67, v79, v67
	v_max3_u32 v67, v69, v70, v67
	v_add_f32_e32 v69, v66, v0
	v_ashrrev_i32_e32 v70, 31, v69
	v_or_b32_e32 v70, 0x80000000, v70
	v_bitop3_b32 v69, v70, s26, v69 bitop3:0x48
	v_or_b32_e32 v69, 0xaf, v69
	v_max_u32_e32 v70, v68, v69
	v_min_u32_e32 v68, v68, v69
	v_max_u32_e32 v69, v71, v68
	v_med3_u32 v71, v71, v84, v68
	v_med3_u32 v79, v84, v85, v68
	v_med3_u32 v84, v85, v72, v68
	v_med3_u32 v72, v72, v73, v68
	v_med3_u32 v73, v73, v80, v68
	v_med3_u32 v80, v80, v81, v68
	v_med3_u32 v81, v81, v74, v68
	v_med3_u32 v74, v74, v75, v68
	v_med3_u32 v75, v75, v82, v68
	v_med3_u32 v82, v82, v83, v68
	v_med3_u32 v83, v83, v76, v68
	v_med3_u32 v76, v76, v77, v68
	v_add_f32_e32 v66, v66, v62
	v_med3_u32 v77, v77, v78, v68
	v_min_u32_e32 v68, v78, v68
	v_ashrrev_i32_e32 v78, 31, v66
	v_or_b32_e32 v78, 0x80000000, v78
	v_bitop3_b32 v66, v78, s26, v66 bitop3:0x48
	v_or_b32_e32 v66, 0xae, v66
	v_max_u32_e32 v78, v70, v66
	v_min_u32_e32 v66, v70, v66
	v_max_u32_e32 v70, v69, v66
	v_med3_u32 v69, v69, v71, v66
	v_med3_u32 v71, v71, v79, v66
	v_med3_u32 v79, v79, v84, v66
	v_med3_u32 v84, v84, v72, v66
	v_med3_u32 v72, v72, v73, v66
	v_med3_u32 v73, v73, v80, v66
	v_med3_u32 v80, v80, v81, v66
	v_med3_u32 v81, v81, v74, v66
	v_med3_u32 v74, v74, v75, v66
	v_med3_u32 v75, v75, v82, v66
	v_med3_u32 v82, v82, v83, v66
	v_med3_u32 v83, v83, v76, v66
	v_med3_u32 v76, v76, v77, v66
	v_min_u32_e32 v66, v77, v66
	v_max3_u32 v66, v67, v68, v66
	v_add_f32_e32 v67, v65, v0
	v_ashrrev_i32_e32 v68, 31, v67
	v_or_b32_e32 v68, 0x80000000, v68
	v_bitop3_b32 v67, v68, s26, v67 bitop3:0x48
	v_or_b32_e32 v67, 0x9f, v67
	v_max_u32_e32 v68, v78, v67
	v_min_u32_e32 v67, v78, v67
	v_max_u32_e32 v77, v70, v67
	v_med3_u32 v70, v70, v69, v67
	v_med3_u32 v69, v69, v71, v67
	v_med3_u32 v71, v71, v79, v67
	v_med3_u32 v78, v79, v84, v67
	v_med3_u32 v79, v84, v72, v67
	v_med3_u32 v72, v72, v73, v67
	v_med3_u32 v73, v73, v80, v67
	v_med3_u32 v80, v80, v81, v67
	v_med3_u32 v81, v81, v74, v67
	v_med3_u32 v74, v74, v75, v67
	v_med3_u32 v75, v75, v82, v67
	v_med3_u32 v82, v82, v83, v67
	v_add_f32_e32 v65, v65, v62
	v_med3_u32 v83, v83, v76, v67
	v_min_u32_e32 v67, v76, v67
	v_ashrrev_i32_e32 v76, 31, v65
	v_or_b32_e32 v76, 0x80000000, v76
	v_bitop3_b32 v65, v76, s26, v65 bitop3:0x48
	v_or_b32_e32 v65, 0x9e, v65
	v_max_u32_e32 v76, v68, v65
	v_min_u32_e32 v65, v68, v65
	v_max_u32_e32 v68, v77, v65
	v_med3_u32 v77, v77, v70, v65
	v_med3_u32 v70, v70, v69, v65
	v_med3_u32 v69, v69, v71, v65
	v_med3_u32 v71, v71, v78, v65
	v_med3_u32 v78, v78, v79, v65
	v_med3_u32 v79, v79, v72, v65
	v_med3_u32 v72, v72, v73, v65
	v_med3_u32 v73, v73, v80, v65
	v_med3_u32 v80, v80, v81, v65
	v_med3_u32 v81, v81, v74, v65
	v_med3_u32 v74, v74, v75, v65
	v_med3_u32 v75, v75, v82, v65
	v_med3_u32 v82, v82, v83, v65
	v_min_u32_e32 v65, v83, v65
	v_max3_u32 v65, v66, v67, v65
	v_add_f32_e32 v66, v64, v0
	v_ashrrev_i32_e32 v67, 31, v66
	v_add_f32_e32 v62, v64, v62
	v_or_b32_e32 v67, 0x80000000, v67
	v_ashrrev_i32_e32 v64, 31, v62
	v_bitop3_b32 v66, v67, s26, v66 bitop3:0x48
	v_or_b32_e32 v64, 0x80000000, v64
	v_or_b32_e32 v66, 0x8f, v66
	v_bitop3_b32 v62, v64, s26, v62 bitop3:0x48
	v_max_u32_e32 v67, v76, v66
	v_min_u32_e32 v66, v76, v66
	v_or_b32_e32 v62, 0x8e, v62
	v_max_u32_e32 v76, v68, v66
	v_min_u32_e32 v66, v68, v66
	v_max_u32_e32 v64, v67, v62
	v_min_u32_e32 v62, v67, v62
	v_max_u32_e32 v68, v77, v66
	v_min_u32_e32 v66, v77, v66
	v_max_u32_e32 v67, v76, v62
	v_min_u32_e32 v62, v76, v62
	v_max_u32_e32 v77, v70, v66
	v_min_u32_e32 v66, v70, v66
	v_max_u32_e32 v76, v68, v62
	v_min_u32_e32 v62, v68, v62
	v_max_u32_e32 v70, v69, v66
	v_min_u32_e32 v66, v69, v66
	v_max_u32_e32 v68, v77, v62
	v_min_u32_e32 v62, v77, v62
	v_max_u32_e32 v69, v71, v66
	v_min_u32_e32 v66, v71, v66
	v_max_u32_e32 v77, v70, v62
	v_min_u32_e32 v62, v70, v62
	v_max_u32_e32 v71, v78, v66
	v_min_u32_e32 v66, v78, v66
	v_max_u32_e32 v70, v69, v62
	v_min_u32_e32 v62, v69, v62
	v_max_u32_e32 v78, v79, v66
	v_min_u32_e32 v66, v79, v66
	v_max_u32_e32 v69, v71, v62
	v_min_u32_e32 v62, v71, v62
	v_max_u32_e32 v79, v72, v66
	v_min_u32_e32 v66, v72, v66
	v_max_u32_e32 v71, v78, v62
	v_min_u32_e32 v62, v78, v62
	v_max_u32_e32 v72, v73, v66
	v_min_u32_e32 v66, v73, v66
	v_max_u32_e32 v78, v79, v62
	v_min_u32_e32 v62, v79, v62
	v_max_u32_e32 v73, v80, v66
	v_min_u32_e32 v66, v80, v66
	v_max_u32_e32 v79, v72, v62
	v_min_u32_e32 v62, v72, v62
	v_max_u32_e32 v80, v81, v66
	v_min_u32_e32 v66, v81, v66
	v_max_u32_e32 v72, v73, v62
	v_min_u32_e32 v62, v73, v62
	v_max_u32_e32 v81, v74, v66
	v_min_u32_e32 v66, v74, v66
	v_max_u32_e32 v73, v80, v62
	v_min_u32_e32 v62, v80, v62
	v_max_u32_e32 v74, v75, v66
	v_min_u32_e32 v66, v75, v66
	v_max_u32_e32 v80, v81, v62
	v_min_u32_e32 v62, v81, v62
	v_max_u32_e32 v75, v82, v66
	v_max_u32_e32 v81, v74, v62
	v_min_u32_e32 v62, v74, v62
	v_min_u32_e32 v66, v82, v66
	v_max_u32_e32 v74, v75, v62
	v_min_u32_e32 v62, v75, v62
	v_add_f32_e32 v63, v63, v0
	v_max3_u32 v62, v65, v66, v62
	v_ashrrev_i32_e32 v65, 31, v63
	v_or_b32_e32 v65, 0x80000000, v65
; __device__ void topk_phase(const Params& p) {
;     ...
;       for (int j = 0; j < 16; ++j) { sa[j] = ord_dec(lists[0][j] & ~127u); sb[j] = ord_dec(lists[1][j] & ~127u); }
;       u32 top[16];
; #pragma unroll
;       for (int j = 0; j < 16; ++j) top[j] = 0u;
; #pragma unroll
;       for (int i = 0; i < 16; ++i)
; #pragma unroll
;         for (int j = 0; j < 16; ++j)
;           if ((i + 1) * (j + 1) <= 16) {
;             const u32 v = (ord_enc(sa[i] + sb[j]) | 255u) ^ (u32)(i * 16 + j);
;             ins16(top, v);
;           }
;       float sc[16];
;       int* idst = p.idx + tok * 128 + h * 16;
; #pragma unroll
;       for (int k4 = 0; k4 < 4; ++k4) {
	v_bitop3_b32 v63, v65, s26, v63 bitop3:0x48
	v_or_b32_e32 v63, 0x7f, v63
	v_max_u32_e32 v65, v64, v63
	v_min_u32_e32 v63, v64, v63
	v_max_u32_e32 v64, v67, v63
	v_med3_u32 v66, v67, v76, v63
	v_med3_u32 v67, v76, v68, v63
	v_med3_u32 v68, v68, v77, v63
	v_med3_u32 v75, v77, v70, v63
	v_med3_u32 v70, v70, v69, v63
	v_med3_u32 v69, v69, v71, v63
	v_med3_u32 v71, v71, v78, v63
	v_med3_u32 v76, v78, v79, v63
	v_med3_u32 v77, v79, v72, v63
	v_med3_u32 v72, v72, v73, v63
	v_med3_u32 v73, v73, v80, v63
	v_med3_u32 v78, v80, v81, v63
	v_add_f32_e32 v60, v60, v0
	v_med3_u32 v79, v81, v74, v63
	v_min_u32_e32 v63, v74, v63
	v_ashrrev_i32_e32 v74, 31, v60
	v_or_b32_e32 v74, 0x80000000, v74
	v_bitop3_b32 v60, v74, s26, v60 bitop3:0x48
	v_or_b32_e32 v60, 0x6f, v60
	v_max_u32_e32 v74, v65, v60
	v_min_u32_e32 v60, v65, v60
	v_max_u32_e32 v65, v64, v60
	v_med3_u32 v64, v64, v66, v60
	v_med3_u32 v66, v66, v67, v60
	v_med3_u32 v67, v67, v68, v60
	v_med3_u32 v68, v68, v75, v60
	v_med3_u32 v75, v75, v70, v60
	v_med3_u32 v70, v70, v69, v60
	v_med3_u32 v69, v69, v71, v60
	v_med3_u32 v71, v71, v76, v60
	v_med3_u32 v76, v76, v77, v60
	v_med3_u32 v77, v77, v72, v60
	v_med3_u32 v72, v72, v73, v60
	v_med3_u32 v73, v73, v78, v60
	v_med3_u32 v78, v78, v79, v60
	v_min_u32_e32 v60, v79, v60
	v_add_f32_e32 v34, v34, v0
	v_max3_u32 v60, v62, v63, v60
	v_ashrrev_i32_e32 v62, 31, v34
	v_or_b32_e32 v62, 0x80000000, v62
	v_bitop3_b32 v34, v62, s26, v34 bitop3:0x48
	v_or_b32_e32 v34, 0x5f, v34
	v_max_u32_e32 v62, v74, v34
	v_min_u32_e32 v34, v74, v34
	v_max_u32_e32 v63, v65, v34
	v_med3_u32 v65, v65, v64, v34
	v_med3_u32 v64, v64, v66, v34
	v_med3_u32 v66, v66, v67, v34
	v_med3_u32 v67, v67, v68, v34
	v_med3_u32 v68, v68, v75, v34
	v_med3_u32 v74, v75, v70, v34
	v_med3_u32 v70, v70, v69, v34
	v_med3_u32 v69, v69, v71, v34
	v_med3_u32 v71, v71, v76, v34
	v_add_f32_e32 v5, v5, v0
	v_med3_u32 v75, v76, v77, v34
	v_min_u32_e32 v34, v77, v34
	v_ashrrev_i32_e32 v77, 31, v5
	v_or_b32_e32 v77, 0x80000000, v77
	v_bitop3_b32 v5, v77, s26, v5 bitop3:0x48
	v_or_b32_e32 v5, 0x4f, v5
	v_max_u32_e32 v77, v62, v5
	v_min_u32_e32 v5, v62, v5
	v_max_u32_e32 v62, v63, v5
	v_med3_u32 v63, v63, v65, v5
	v_med3_u32 v65, v65, v64, v5
	v_med3_u32 v64, v64, v66, v5
	v_med3_u32 v66, v66, v67, v5
	v_med3_u32 v67, v67, v68, v5
	v_med3_u32 v68, v68, v74, v5
	v_med3_u32 v74, v74, v70, v5
	v_med3_u32 v70, v70, v69, v5
	v_med3_u32 v69, v69, v71, v5
	v_min_u32_e32 v5, v71, v5
	v_max_u32_e32 v76, v72, v34
	v_min_u32_e32 v34, v72, v34
	v_max_u32_e32 v71, v75, v5
	v_min_u32_e32 v5, v75, v5
	v_max_u32_e32 v72, v73, v34
	v_min_u32_e32 v34, v73, v34
	v_max_u32_e32 v75, v76, v5
	v_min_u32_e32 v5, v76, v5
	v_max_u32_e32 v73, v78, v34
	v_max_u32_e32 v76, v72, v5
	v_min_u32_e32 v5, v72, v5
	v_min_u32_e32 v34, v78, v34
	v_max_u32_e32 v72, v73, v5
	v_min_u32_e32 v5, v73, v5
	v_add_f32_e32 v4, v4, v0
	v_max3_u32 v5, v60, v34, v5
	v_ashrrev_i32_e32 v34, 31, v4
	v_bitop3_b32 v4, v34, v4, s18 bitop3:0x36
	v_and_or_b32 v4, v4, s26, 63
	v_max_u32_e32 v34, v77, v4
	v_min_u32_e32 v4, v77, v4
	v_max_u32_e32 v60, v62, v4
	v_med3_u32 v62, v62, v63, v4
	v_med3_u32 v63, v63, v65, v4
	v_med3_u32 v65, v65, v64, v4
	v_med3_u32 v64, v64, v66, v4
	v_med3_u32 v66, v66, v67, v4
	v_med3_u32 v67, v67, v68, v4
	v_med3_u32 v68, v68, v74, v4
	v_med3_u32 v73, v74, v70, v4
	v_med3_u32 v70, v70, v69, v4
	v_med3_u32 v69, v69, v71, v4
	v_med3_u32 v71, v71, v75, v4
	v_med3_u32 v74, v75, v76, v4
	v_add_f32_e32 v3, v3, v0
	v_med3_u32 v75, v76, v72, v4
	v_min_u32_e32 v4, v72, v4
	v_ashrrev_i32_e32 v72, 31, v3
	v_bitop3_b32 v3, v72, v3, s18 bitop3:0x36
	v_and_or_b32 v3, v3, s26, 47
	v_max_u32_e32 v72, v34, v3
	v_min_u32_e32 v3, v34, v3
	v_max_u32_e32 v34, v60, v3
	v_med3_u32 v60, v60, v62, v3
	v_med3_u32 v62, v62, v63, v3
	v_med3_u32 v63, v63, v65, v3
	v_med3_u32 v65, v65, v64, v3
	v_med3_u32 v64, v64, v66, v3
	v_med3_u32 v66, v66, v67, v3
	v_med3_u32 v67, v67, v68, v3
	v_med3_u32 v68, v68, v73, v3
	v_med3_u32 v73, v73, v70, v3
	v_med3_u32 v70, v70, v69, v3
	v_med3_u32 v69, v69, v71, v3
	v_med3_u32 v71, v71, v74, v3
	v_med3_u32 v74, v74, v75, v3
	v_min_u32_e32 v3, v75, v3
	v_add_f32_e32 v2, v2, v0
	v_max3_u32 v3, v5, v4, v3
	v_ashrrev_i32_e32 v4, 31, v2
	v_bitop3_b32 v2, v4, v2, s18 bitop3:0x36
	v_and_or_b32 v2, v2, s26, 31
	v_max_u32_e32 v4, v72, v2
	v_min_u32_e32 v2, v72, v2
	v_max_u32_e32 v5, v34, v2
	v_med3_u32 v34, v34, v60, v2
	v_med3_u32 v60, v60, v62, v2
	v_med3_u32 v62, v62, v63, v2
	v_med3_u32 v63, v63, v65, v2
	v_med3_u32 v65, v65, v64, v2
	v_med3_u32 v64, v64, v66, v2
	v_bitop3_b32 v1, v1, v21, s24 bitop3:0x78
	v_med3_u32 v66, v66, v67, v2
	v_med3_u32 v67, v67, v68, v2
	v_add_f32_e32 v0, v1, v0
	v_med3_u32 v68, v68, v73, v2
	v_ashrrev_i32_e32 v1, 31, v0
	v_med3_u32 v77, v73, v70, v2
	v_bitop3_b32 v0, v1, v0, s18 bitop3:0x36
	v_med3_u32 v78, v70, v69, v2
	v_and_or_b32 v0, v0, s26, 15
	v_med3_u32 v79, v69, v71, v2
	v_min_u32_e32 v2, v71, v2
	v_max_u32_e32 v73, v4, v0
	v_min_u32_e32 v0, v4, v0
	v_max_u32_e32 v80, v74, v2
	v_min_u32_e32 v2, v74, v2
	v_max_u32_e32 v74, v5, v0
	v_min_u32_e32 v0, v5, v0
	v_max_u32_e32 v75, v34, v0
	v_med3_u32 v76, v34, v60, v0
	v_med3_u32 v69, v60, v62, v0
	v_med3_u32 v70, v62, v63, v0
	v_med3_u32 v71, v63, v65, v0
	v_med3_u32 v72, v65, v64, v0
	v_med3_u32 v65, v64, v66, v0
	v_med3_u32 v66, v66, v67, v0
	v_med3_u32 v67, v67, v68, v0
	v_med3_u32 v68, v68, v77, v0
	v_med3_u32 v60, v77, v78, v0
	v_med3_u32 v62, v78, v79, v0
	v_med3_u32 v63, v79, v80, v0
	v_min_u32_e32 v0, v80, v0
	v_max3_u32 v64, v3, v2, v0
	v_lshlrev_b32_e32 v34, 4, v59
	s_and_saveexec_b64 s[10:11], s[2:3]
	s_xor_b64 s[10:11], exec, s[10:11]
	s_cbranch_execz .LBB0_792
; __device__ void topk_phase(const Params& p) {
;     ...
;           const float sv = ord_dec(top[k] & ~255u);
;           sc[k] = sv;
;         }
;         if (lh == 0) *(int4*)(idst + k4 * 4) = make_int4(ex[0], ex[1], ex[2], ex[3]);
;       }
;       const float rs = 1.f;
;       if (lh == 1) {
;         float4* dst = (float4*)(p.gate + tok * 128 + h * 16);
; #pragma unroll
;         for (int k = 0; k < 4; ++k) dst[k] = make_float4(sc[4 * k] * rs, sc[4 * k + 1] * rs, sc[4 * k + 2] * rs, sc[4 * k + 3] * rs);
;       }
	v_cmp_lt_i32_e32 vcc, -1, v76
	v_lshl_add_u64 v[4:5], v[34:35], 2, v[44:45]
	s_nop 0
	v_cndmask_b32_e64 v0, v58, -1, vcc
	v_cmp_lt_i32_e32 vcc, -1, v75
	v_bitop3_b32 v9, v0, v76, s26 bitop3:0x78
	s_nop 0
	v_cndmask_b32_e64 v0, v58, -1, vcc
	v_cmp_lt_i32_e32 vcc, -1, v74
	v_bitop3_b32 v8, v0, v75, s26 bitop3:0x78
	s_nop 0
	v_cndmask_b32_e64 v0, v58, -1, vcc
	v_cmp_lt_i32_e32 vcc, -1, v73
	v_bitop3_b32 v7, v0, v74, s26 bitop3:0x78
	s_nop 0
	v_cndmask_b32_e64 v0, v58, -1, vcc
	v_cmp_lt_i32_e32 vcc, -1, v72
	v_bitop3_b32 v6, v0, v73, s26 bitop3:0x78
	s_nop 0
	v_cndmask_b32_e64 v0, v58, -1, vcc
	v_cmp_lt_i32_e32 vcc, -1, v71
	v_bitop3_b32 v13, v0, v72, s26 bitop3:0x78
	s_nop 0
	v_cndmask_b32_e64 v0, v58, -1, vcc
	v_cmp_lt_i32_e32 vcc, -1, v70
	v_bitop3_b32 v12, v0, v71, s26 bitop3:0x78
	s_nop 0
	v_cndmask_b32_e64 v0, v58, -1, vcc
	v_cmp_lt_i32_e32 vcc, -1, v69
	v_bitop3_b32 v11, v0, v70, s26 bitop3:0x78
	s_nop 0
	v_cndmask_b32_e64 v0, v58, -1, vcc
	v_cmp_lt_i32_e32 vcc, -1, v68
	v_bitop3_b32 v10, v0, v69, s26 bitop3:0x78
	s_nop 0
	v_cndmask_b32_e64 v0, v58, -1, vcc
	v_cmp_lt_i32_e32 vcc, -1, v67
	v_bitop3_b32 v17, v0, v68, s26 bitop3:0x78
	s_nop 0
	v_cndmask_b32_e64 v0, v58, -1, vcc
	v_cmp_lt_i32_e32 vcc, -1, v66
	v_bitop3_b32 v16, v0, v67, s26 bitop3:0x78
	s_nop 0
	v_cndmask_b32_e64 v0, v58, -1, vcc
	v_cmp_lt_i32_e32 vcc, -1, v65
	v_bitop3_b32 v15, v0, v66, s26 bitop3:0x78
	s_nop 0
	v_cndmask_b32_e64 v0, v58, -1, vcc
	v_cmp_lt_i32_e32 vcc, -1, v64
	v_bitop3_b32 v14, v0, v65, s26 bitop3:0x78
	global_store_dwordx4 v[4:5], v[6:9], off
	global_store_dwordx4 v[4:5], v[10:13], off offset:16
	global_store_dwordx4 v[4:5], v[14:17], off offset:32
	v_cndmask_b32_e64 v0, v58, -1, vcc
	v_cmp_lt_i32_e32 vcc, -1, v63
	v_bitop3_b32 v3, v0, v64, s26 bitop3:0x78
	s_nop 0
	v_cndmask_b32_e64 v0, v58, -1, vcc
	v_cmp_lt_i32_e32 vcc, -1, v62
	v_bitop3_b32 v2, v0, v63, s26 bitop3:0x78
	s_nop 0
	v_cndmask_b32_e64 v0, v58, -1, vcc
	v_cmp_lt_i32_e32 vcc, -1, v60
	v_bitop3_b32 v1, v0, v62, s26 bitop3:0x78
	s_nop 0
	v_cndmask_b32_e64 v0, v58, -1, vcc
	v_bitop3_b32 v0, v0, v60, s26 bitop3:0x78

; __device__ __forceinline__ int tid_op() { int t = threadIdx.x & 255; asm volatile("" : "+v"(t)); return t; }
; __device__ __forceinline__ int vb_op() { return (int)(blockIdx.x << 1) | sub_op(); }
; __device__ void peer_phase(const Params& p) {
;   const int tid = tid_op(), lane = tid & 63, wv = tid >> 6;
;   const int gw = vb_op() * 4 + wv, nw = p.nblk * 4;
;   const u16* hn = p.xn;
;   const unsigned char* down4 = (const unsigned char*)p.down;
;   const unsigned char* up4 = (const unsigned char*)p.up;
;   int eidn0 = 0, eidn1 = 0;
;   if (gw < T_TOK) { eidn0 = p.idx[(size_t)gw * 128 + lane]; eidn1 = p.idx[(size_t)gw * 128 + 64 + lane]; }
.LBB0_846:
	s_or_b64 exec, exec, s[0:1]
	v_readfirstlane_b32 s0, v252
	s_lshr_b32 s0, s0, 6
	s_and_b32 s0, s0, 0x3fffffc
	s_waitcnt lgkmcnt(0)
	s_barrier
	s_or_b32 s0, s0, s23
	v_ashrrev_i32_e32 v0, 6, v167
	v_add_u32_e32 v80, s0, v0
	s_mov_b32 s6, 0x8000
	v_cmp_gt_i32_e32 vcc, s6, v80
	s_and_saveexec_b64 s[0:1], vcc
	s_cbranch_execz .LBB0_867
	v_readlane_b32 s36, v253, 55
	v_readlane_b32 s44, v253, 63
	v_readlane_b32 s45, v254, 0
	v_ashrrev_i32_e32 v81, 31, v80
	v_readlane_b32 s46, v254, 1
	v_readlane_b32 s47, v254, 2
	v_readlane_b32 s48, v254, 3
	v_readlane_b32 s49, v254, 4
	v_readlane_b32 s50, v254, 5
	v_readlane_b32 s51, v254, 6
	s_mov_b64 s[8:9], s[44:45]
	v_and_b32_e32 v88, 63, v167
	v_lshlrev_b64 v[0:1], 9, v[80:81]
	s_mov_b64 s[14:15], s[50:51]
	v_lshl_add_u64 v[0:1], s[14:15], 0, v[0:1]
	v_lshlrev_b32_e32 v64, 2, v88
	v_mov_b32_e32 v65, 0
	v_lshl_add_u64 v[0:1], v[0:1], 0, v[64:65]
	global_load_dword v86, v[0:1], off
	global_load_dword v82, v[0:1], off offset:256
	v_mbcnt_hi_u32_b32 v1, -1, v151
	v_and_b32_e32 v2, 64, v1
	v_add_u32_e32 v2, 64, v2
	v_xor_b32_e32 v3, 32, v1
	v_cmp_lt_i32_e32 vcc, v3, v2
	v_and_b32_e32 v4, 63, v1
	v_readlane_b32 s37, v253, 56
	v_cndmask_b32_e32 v3, v1, v3, vcc
	v_lshlrev_b32_e32 v89, 2, v3
	v_xor_b32_e32 v3, 16, v1
	v_cmp_lt_i32_e32 vcc, v3, v2
	v_readlane_b32 s38, v253, 57
	v_readlane_b32 s39, v253, 58
	v_cndmask_b32_e32 v3, v1, v3, vcc
	v_lshlrev_b32_e32 v90, 2, v3
	v_xor_b32_e32 v3, 8, v1
	v_cmp_lt_i32_e32 vcc, v3, v2
	v_readlane_b32 s40, v253, 59
	v_readlane_b32 s41, v253, 60
	v_cndmask_b32_e32 v3, v1, v3, vcc
	v_lshlrev_b32_e32 v91, 2, v3
	v_xor_b32_e32 v3, 4, v1
	v_cmp_lt_i32_e32 vcc, v3, v2
	v_readlane_b32 s42, v253, 61
	v_readlane_b32 s43, v253, 62
	v_cndmask_b32_e32 v3, v1, v3, vcc
	v_lshlrev_b32_e32 v92, 2, v3
	v_xor_b32_e32 v3, 2, v1
	v_cmp_lt_i32_e32 vcc, v3, v2
	s_mov_b64 s[10:11], s[46:47]
	s_mov_b64 s[12:13], s[48:49]
	v_cndmask_b32_e32 v3, v1, v3, vcc
	v_lshlrev_b32_e32 v93, 2, v3
	v_xor_b32_e32 v3, 1, v1
	v_cmp_lt_i32_e32 vcc, v3, v2
	v_readlane_b32 s36, v253, 39
	v_readlane_b32 s37, v253, 40
	v_cndmask_b32_e32 v2, v1, v3, vcc
	v_cmp_ne_u32_e32 vcc, 63, v4
	v_readlane_b32 s38, v253, 41
	v_readlane_b32 s39, v253, 42
	v_addc_co_u32_e32 v5, vcc, 0, v1, vcc
	v_cmp_gt_u32_e32 vcc, 62, v4
	v_readlane_b32 s40, v253, 43
	v_readlane_b32 s41, v253, 44
	v_readlane_b32 s42, v253, 45
	v_readlane_b32 s43, v253, 46
	v_readlane_b32 s44, v253, 47
	v_readlane_b32 s45, v253, 48
	v_readlane_b32 s46, v253, 49
	v_readlane_b32 s47, v253, 50
	v_readlane_b32 s48, v253, 51
	v_readlane_b32 s49, v253, 52
	v_readlane_b32 s50, v253, 53
	v_readlane_b32 s51, v253, 54
	s_mov_b64 s[0:1], s[36:37]
	v_lshlrev_b32_e32 v95, 2, v5
	v_cndmask_b32_e64 v5, 0, 2, vcc
	v_cmp_gt_u32_e32 vcc, 61, v4
	v_lshlrev_b32_e32 v0, 3, v88
	s_mov_b64 s[2:3], s[38:39]
	v_cndmask_b32_e64 v4, 0, 3, vcc
	v_readlane_b32 s36, v253, 23
	v_lshlrev_b32_e32 v94, 2, v2
	v_lshlrev_b32_e32 v2, 4, v88
	v_mov_b32_e32 v3, v65
	v_add_lshl_u32 v97, v4, v1, 2
	v_or_b32_e32 v4, 0x400, v0
	v_or_b32_e32 v6, 0x600, v0
	v_readlane_b32 s42, v253, 29
	v_readlane_b32 s43, v253, 30
	v_lshl_add_u64 v[66:67], s[0:1], 0, v[2:3]
	v_add_lshl_u32 v96, v5, v1, 2
	v_lshl_add_u64 v[68:69], s[2:3], 0, v[2:3]
	v_lshl_add_u64 v[70:71], s[14:15], 0, v[64:65]
	v_lshl_add_u64 v[72:73], s[8:9], 0, v[64:65]
	v_lshl_add_u64 v[74:75], s[42:43], 0, v[2:3]
	s_mov_b64 s[2:3], 0
	s_movk_i32 s7, 0x1100
	s_mov_b32 s8, 0x42fe0000
	s_movk_i32 s9, 0x7fff
	v_mov_b32_e32 v98, 0x358637bd
	s_mov_b32 s10, 0x800000
	s_mov_b32 s11, 0xc0c0500
	s_mov_b32 s12, 0x378e98ab
	s_mov_b32 s13, 0x3b7cd369
	s_mov_b32 s14, 0xbcc618b2
	s_mov_b32 s15, 0x3dda74e4
	s_mov_b32 s16, 0x3f228afd
	s_mov_b32 s17, 0x3e03c728
	s_mov_b32 s18, 0xbfb8aa3b
	s_mov_b32 s19, 0x42ce8ed0
	s_mov_b32 s20, 0xc2b17218
	v_mov_b32_e32 v99, 0x3ba10414
	s_brev_b32 s21, -2
	s_mov_b32 s23, 0xc06010c
	s_mov_b32 s24, 0x5010400
	s_mov_b32 s25, 0x7030602
	s_mov_b32 s26, 0x5040100
	s_mov_b32 s27, 0x7060302
	s_mov_b32 s28, 0xc060c00
	v_lshlrev_b32_e32 v64, 2, v0
	v_lshlrev_b32_e32 v76, 2, v4
	v_lshlrev_b32_e32 v78, 2, v6
	v_mov_b32_e32 v100, 0xb9c68948
	v_mov_b32_e32 v101, 0x7f800000
	v_readlane_b32 s37, v253, 24
	v_readlane_b32 s38, v253, 25
	v_readlane_b32 s39, v253, 26
	v_readlane_b32 s40, v253, 27
	v_readlane_b32 s41, v253, 28
	v_readlane_b32 s44, v253, 31
	v_readlane_b32 s45, v253, 32
	v_readlane_b32 s46, v253, 33
	v_readlane_b32 s47, v253, 34
	v_readlane_b32 s48, v253, 35
	v_readlane_b32 s49, v253, 36
	v_readlane_b32 s50, v253, 37
	v_readlane_b32 s51, v253, 38
	v_mov_b32_e32 v235, v80

; __device__ void peer_phase(const Params& p) {
;     ...
;       const float sv = gg[hf] * rinv;
;       float m = sv;
; #pragma unroll
;       for (int o = 8; o >= 1; o >>= 1) m = fmaxf(m, __shfl_xor(m, o));
;       const float ev = __expf(sv - m);
;       float sm = ev;
; #pragma unroll
;       for (int o = 8; o >= 1; o >>= 1) sm += __shfl_xor(sm, o);
;       gg[hf] = ev / sm;
;     }
;     const float ds0 = p.dscale[eid[0]], ds1 = p.dscale[eid[1]];
;     const float us0 = p.uscale[eid[0]], us1 = p.uscale[eid[1]];
; #pragma unroll
;     for (int hf = 0; hf < 2; ++hf) {
;       int acti = 0;
;       for (int e = 0; e < 64; e += 16) {
;         uint4 d[16];
; #pragma unroll
;         for (int u = 0; u < 16; ++u) {
;           const int id = __builtin_amdgcn_readlane(eid[hf], e + u);
;           d[u] = ((const uint4*)(down4 + (size_t)id * 1024))[lane];
;         }
; #pragma unroll
;         for (int u = 0; u < 16; ++u) {
;           const u32 w[4] = {d[u].x, d[u].y, d[u].z, d[u].w};
;           int s0 = 0, s1 = 0;
; #pragma unroll
;           for (int k = 0; k < 4; ++k) {
;             s0 = __builtin_amdgcn_sdot4((int)(w[k] & 0x0F0F0F0Fu), hq[2 * k], s0, false);
;             s1 = __builtin_amdgcn_sdot4((int)((w[k] >> 4) & 0x0F0F0F0Fu), hq[2 * k + 1], s1, false);
;           }
;           const int sI = wave_sum_i(s0 + s1);
;           if (lane == e + u) acti = sI;
;         }
;       }
;       const float act = ((float)acti - 7.5f * (float)hsum) * sh * (hf == 0 ? ds0 : ds1);
;       gg[hf] *= 0.5f * act * (1.f + erff(act * 0.70710678118654752f)) * (hf == 0 ? us0 : us1);
;     }
;     float gmax = fmaxf(fabsf(gg[0]), fabsf(gg[1]));
; #pragma unroll
;     for (int o = 32; o >= 1; o >>= 1) gmax = fmaxf(gmax, __shfl_xor(gmax, o));
;     const float ginv = gmax > 0.f ? 127.f / gmax : 0.f;
;     int gq[2], gpk[2];
; #pragma unroll
;     for (int hf = 0; hf < 2; ++hf) {
;       gq[hf] = (int)rintf(gg[hf] * ginv);
;       const int b0 = gq[hf] & 0xFF;
;       const int b1 = __shfl_down(gq[hf], 1) & 0xFF, b2 = __shfl_down(gq[hf], 2) & 0xFF, b3 = __shfl_down(gq[hf], 3) & 0xFF;
;       gpk[hf] = b0 | (b1 << 8) | (b2 << 16) | (b3 << 24);
;     }
;     const int gqsum = wave_sum_i(gq[0] + gq[1]);
.LBB0_860:
	s_andn2_saveexec_b64 s[0:1], s[0:1]
	v_mul_f32_e32 v6, v3, v3
	v_fmamk_f32 v7, v6, 0xba1345e1, v99
	v_fmaak_f32 v7, v6, v7, 0xbcdac9b8
	v_fmaak_f32 v7, v6, v7, 0x3de703be
	v_fmaak_f32 v7, v6, v7, 0xbec09330
	v_fmaak_f32 v6, v6, v7, 0x3e0375d0
	v_fma_f32 v6, |v3|, v6, |v3|
	s_or_b64 exec, exec, s[0:1]
	v_add_f32_e32 v7, v17, v18
	v_div_scale_f32 v8, s[0:1], v7, v7, v4
	v_rcp_f32_e32 v9, v8
	v_div_scale_f32 v10, vcc, v4, v7, v4
	v_bfi_b32 v3, s21, v6, v3
	v_fma_f32 v11, -v8, v9, 1.0
	v_fmac_f32_e32 v9, v11, v9
	v_mul_f32_e32 v11, v10, v9
	v_fma_f32 v12, -v8, v11, v10
	v_fmac_f32_e32 v11, v12, v9
	v_fma_f32 v8, -v8, v11, v10
	v_div_fmas_f32 v8, v8, v9, v11
	v_div_fixup_f32 v4, v8, v7, v4
	v_bfi_b32 v8, s21, v19, v16
	v_mul_f32_e32 v7, 0.5, v15
	v_add_f32_e32 v8, 1.0, v8
	v_mul_f32_e32 v7, v7, v8
	v_add_f32_e32 v8, v13, v14
	v_div_scale_f32 v9, s[0:1], v8, v8, v2
	v_rcp_f32_e32 v10, v9
	v_mul_f32_e32 v1, v1, v7
	v_mul_f32_e32 v1, v4, v1
	v_mul_f32_e32 v4, 0.5, v5
	v_fma_f32 v5, -v9, v10, 1.0
	v_fmac_f32_e32 v10, v5, v10
	v_div_scale_f32 v5, vcc, v2, v8, v2
	v_mul_f32_e32 v7, v5, v10
	v_fma_f32 v11, -v9, v7, v5
	v_fmac_f32_e32 v7, v11, v10
	v_fma_f32 v5, -v9, v7, v5
	v_add_f32_e32 v3, 1.0, v3
	v_div_fmas_f32 v5, v5, v10, v7
	v_mul_f32_e32 v3, v4, v3
	v_div_fixup_f32 v2, v5, v8, v2
	v_mul_f32_e32 v0, v0, v3
	v_mul_f32_e32 v77, v2, v0
	v_lshlrev_b64 v[230:231], 9, v[80:81]
	v_lshl_add_u64 v[230:231], v[72:73], 0, v[230:231]
	global_store_dword v[230:231], v1, off
	global_store_dword v[230:231], v77, off offset:256
	v_mov_b32_e32 v86, v102
	v_mov_b32_e32 v82, v85
	v_mov_b32_e32 v80, v84
	s_andn2_b64 exec, exec, s[2:3]
	s_cbranch_execnz .LBB0_848
	s_mov_b64 exec, -1
	s_mov_b64 s[2:3], 0
	v_mov_b32_e32 v80, v235
	v_ashrrev_i32_e32 v81, 31, v80
	v_lshlrev_b64 v[230:231], 9, v[80:81]
	v_lshl_add_u64 v[232:233], v[70:71], 0, v[230:231]
	v_lshl_add_u64 v[230:231], v[72:73], 0, v[230:231]
	s_waitcnt vmcnt(0)
	buffer_inv sc1
	s_waitcnt vmcnt(0)
	global_load_dword v86, v[232:233], off
	global_load_dword v82, v[232:233], off offset:256
	global_load_dword v236, v[230:231], off
	global_load_dword v237, v[230:231], off offset:256
	s_waitcnt vmcnt(0)
.Lp9_up_top:
	v_mov_b32_e32 v1, v236
	v_mov_b32_e32 v77, v237
	v_ashrrev_i32_e32 v81, 31, v80
	v_add_u32_e32 v84, s22, v80
	v_mov_b32_e32 v85, v82
	v_mov_b32_e32 v102, v86
	v_cmp_gt_i32_e64 s[0:1], s6, v84
	s_and_saveexec_b64 s[4:5], s[0:1]
	s_cbranch_execz .Lp9_up_nonext
	v_ashrrev_i32_e32 v85, 31, v84
	v_lshlrev_b64 v[230:231], 9, v[84:85]
	v_lshl_add_u64 v[232:233], v[70:71], 0, v[230:231]
	v_lshl_add_u64 v[230:231], v[72:73], 0, v[230:231]
	global_load_dword v102, v[232:233], off
	global_load_dword v85, v[232:233], off offset:256
	global_load_dword v236, v[230:231], off
	global_load_dword v237, v[230:231], off offset:256
.Lp9_up_nonext:
	s_or_b64 exec, exec, s[4:5]
	v_cmp_lt_i32_e32 vcc, s9, v84
	s_and_b64 s[0:1], exec, vcc
	s_or_b64 s[2:3], s[0:1], s[2:3]
	v_max_f32_e64 v0, |v1|, |v77|
	ds_bpermute_b32 v2, v89, v0
	v_mov_b32_e32 v83, 0
	v_mov_b32_e32 v87, 0
	v_mov_b32_e32 v103, 0
	v_mov_b32_e32 v104, 0
	s_waitcnt lgkmcnt(0)
	v_max_f32_e32 v2, v2, v2
	v_max_f32_e32 v0, v0, v2
	ds_bpermute_b32 v2, v90, v0
	v_mov_b32_e32 v105, 0
	v_mov_b32_e32 v106, 0
	v_mov_b32_e32 v107, 0
	v_mov_b32_e32 v108, 0
	s_waitcnt lgkmcnt(0)
	v_max_f32_e32 v2, v2, v2
	v_max_f32_e32 v0, v0, v2
	ds_bpermute_b32 v2, v91, v0
	v_mov_b32_e32 v110, 0
	v_mov_b32_e32 v111, 0
	v_mov_b32_e32 v113, 0
	v_mov_b32_e32 v112, 0
	s_waitcnt lgkmcnt(0)
	v_max_f32_e32 v2, v2, v2
	v_max_f32_e32 v0, v0, v2
	ds_bpermute_b32 v2, v92, v0
	v_mov_b32_e32 v114, 0
	v_mov_b32_e32 v115, 0
	v_mov_b32_e32 v117, 0
	v_mov_b32_e32 v116, 0
	s_waitcnt lgkmcnt(0)
	v_max_f32_e32 v2, v2, v2
	v_max_f32_e32 v0, v0, v2
	ds_bpermute_b32 v2, v93, v0
	v_mov_b32_e32 v118, 0
	v_mov_b32_e32 v119, 0
	v_mov_b32_e32 v121, 0
	v_mov_b32_e32 v120, 0
	s_waitcnt lgkmcnt(0)
	v_max_f32_e32 v2, v2, v2
	v_max_f32_e32 v0, v0, v2
	ds_bpermute_b32 v2, v94, v0
	v_mov_b32_e32 v122, 0
	v_mov_b32_e32 v123, 0
	v_mov_b32_e32 v125, 0
	v_mov_b32_e32 v124, 0
	s_waitcnt lgkmcnt(0)
	v_max_f32_e32 v2, v2, v2
	v_max_f32_e32 v109, v0, v2
	v_div_scale_f32 v0, s[0:1], v109, v109, s8
	v_rcp_f32_e32 v2, v0
	s_mov_b32 s0, 0
	v_mov_b32_e32 v126, 0
	v_mov_b32_e32 v127, 0
	v_fma_f32 v3, -v0, v2, 1.0
	v_fmac_f32_e32 v2, v3, v2
	v_div_scale_f32 v3, vcc, s8, v109, s8
	v_mul_f32_e32 v4, v3, v2
	v_fma_f32 v5, -v0, v4, v3
	v_fmac_f32_e32 v4, v5, v2
	v_fma_f32 v0, -v0, v4, v3
	v_div_fmas_f32 v0, v0, v2, v4
	v_div_fixup_f32 v0, v0, v109, s8
	v_cmp_lt_f32_e32 vcc, 0, v109
	v_mov_b32_e32 v129, 0
	v_mov_b32_e32 v128, 0
	v_cndmask_b32_e32 v134, 0, v0, vcc
	v_mul_f32_e32 v0, v1, v134
	v_rndne_f32_e32 v0, v0
	v_cvt_i32_f32_e32 v79, v0
	v_mov_b32_e32 v130, 0
	v_mov_b32_e32 v131, 0
	v_mov_b32_e32 v133, 0
	ds_bpermute_b32 v0, v95, v79
	ds_bpermute_b32 v1, v96, v79
	ds_bpermute_b32 v2, v97, v79
	v_and_b32_e32 v3, 0xff, v79
	v_mov_b32_e32 v132, 0
	s_waitcnt lgkmcnt(2)
	v_lshlrev_b32_e32 v0, 8, v0
	s_waitcnt lgkmcnt(1)
	v_lshlrev_b32_e32 v1, 16, v1
	s_waitcnt lgkmcnt(0)
	v_lshlrev_b32_e32 v2, 24, v2
	v_perm_b32 v0, v1, v0, s23
	v_or3_b32 v135, v0, v3, v2
